# f32 residual-stream epilogue stores (EpiResid) write-through sc1: less dirty L2 to flush at the grid barrier
# baseline (speedup 1.0000x reference)
.LBB0_355:
	v_lshl_or_b32 v144, s56, 8, v154
	v_ashrrev_i32_e32 v145, 31, v144
	v_lshl_add_u32 v146, s55, 8, v152
	v_lshlrev_b64 v[144:145], 2, v[144:145]
	v_ashrrev_i32_e32 v147, 31, v146
	v_lshl_add_u64 v[170:171], s[20:21], 0, v[144:145]
	v_lshlrev_b64 v[148:149], 12, v[146:147]
	global_load_dwordx4 v[158:161], v[170:171], off
	v_lshl_add_u64 v[148:149], s[16:17], 0, v[148:149]
	v_lshl_add_u64 v[172:173], v[148:149], 0, v[144:145]
	global_load_dwordx4 v[162:165], v[172:173], off
	global_load_dwordx4 v[166:169], v[170:171], off offset:16
	v_add_u32_e32 v148, 0x100, v146
	v_ashrrev_i32_e32 v149, 31, v148
	v_lshlrev_b64 v[148:149], 12, v[148:149]
	v_lshl_add_u64 v[148:149], s[10:11], 0, v[148:149]
	v_lshl_add_u64 v[174:175], v[148:149], 0, v[144:145]
	s_and_b64 vcc, exec, s[6:7]
	s_mov_b64 s[6:7], -1
	s_waitcnt vmcnt(0)
	v_pk_mul_f32 v[148:149], v[160:161], 0.5 op_sel_hi:[1,0]
	v_pk_mul_f32 v[150:151], v[158:159], 0.5 op_sel_hi:[1,0]
	v_pk_fma_f32 v[126:127], v[126:127], v[148:149], v[164:165]
	v_pk_fma_f32 v[124:125], v[124:125], v[150:151], v[162:163]
	global_store_dwordx4 v[174:175], v[124:127], off sc1
	global_load_dwordx4 v[158:161], v[172:173], off offset:16
	global_load_dwordx4 v[162:165], v[170:171], off offset:512
	v_pk_mul_f32 v[124:125], v[168:169], 0.5 op_sel_hi:[1,0]
	v_pk_mul_f32 v[126:127], v[166:167], 0.5 op_sel_hi:[1,0]
	s_waitcnt vmcnt(1)
	v_pk_fma_f32 v[122:123], v[122:123], v[124:125], v[160:161]
	v_pk_fma_f32 v[120:121], v[120:121], v[126:127], v[158:159]
	global_store_dwordx4 v[174:175], v[120:123], off offset:16 sc1
	global_load_dwordx4 v[158:161], v[172:173], off offset:512
	global_load_dwordx4 v[166:169], v[170:171], off offset:528
	s_waitcnt vmcnt(3)
	v_pk_mul_f32 v[120:121], v[164:165], 0.5 op_sel_hi:[1,0]
	v_pk_mul_f32 v[122:123], v[162:163], 0.5 op_sel_hi:[1,0]
	s_waitcnt vmcnt(1)
	v_pk_fma_f32 v[118:119], v[118:119], v[120:121], v[160:161]
	v_pk_fma_f32 v[116:117], v[116:117], v[122:123], v[158:159]
	global_store_dwordx4 v[174:175], v[116:119], off offset:512 sc1
	global_load_dwordx4 v[158:161], v[172:173], off offset:528
	s_nop 0
	v_or_b32_e32 v116, 16, v146
	v_ashrrev_i32_e32 v117, 31, v116
	v_lshlrev_b64 v[116:117], 12, v[116:117]
	v_lshl_add_u64 v[116:117], s[16:17], 0, v[116:117]
	v_lshl_add_u64 v[162:163], v[116:117], 0, v[144:145]
	s_waitcnt vmcnt(2)
	v_pk_mul_f32 v[116:117], v[168:169], 0.5 op_sel_hi:[1,0]
	v_pk_mul_f32 v[118:119], v[166:167], 0.5 op_sel_hi:[1,0]
	s_waitcnt vmcnt(0)
	v_pk_fma_f32 v[110:111], v[110:111], v[116:117], v[160:161]
	v_pk_fma_f32 v[108:109], v[108:109], v[118:119], v[158:159]
	global_store_dwordx4 v[174:175], v[108:111], off offset:528 sc1
	global_load_dwordx4 v[108:111], v[162:163], off
	v_add_u32_e32 v158, 0x110, v146
	v_ashrrev_i32_e32 v159, 31, v158
	v_lshlrev_b64 v[158:159], 12, v[158:159]
	v_lshl_add_u64 v[158:159], s[10:11], 0, v[158:159]
	v_lshl_add_u64 v[158:159], v[158:159], 0, v[144:145]
	s_waitcnt vmcnt(0)
	v_pk_fma_f32 v[110:111], v[114:115], v[148:149], v[110:111]
	v_pk_fma_f32 v[108:109], v[112:113], v[150:151], v[108:109]
	global_store_dwordx4 v[158:159], v[108:111], off sc1
	global_load_dwordx4 v[108:111], v[162:163], off offset:16
	s_waitcnt vmcnt(0)
	v_pk_fma_f32 v[106:107], v[106:107], v[124:125], v[110:111]
	v_pk_fma_f32 v[104:105], v[104:105], v[126:127], v[108:109]
	global_store_dwordx4 v[158:159], v[104:107], off offset:16 sc1
	global_load_dwordx4 v[104:107], v[162:163], off offset:512
	s_waitcnt vmcnt(0)
	v_pk_fma_f32 v[102:103], v[102:103], v[120:121], v[106:107]
	v_pk_fma_f32 v[100:101], v[100:101], v[122:123], v[104:105]
	global_store_dwordx4 v[158:159], v[100:103], off offset:512 sc1
	global_load_dwordx4 v[100:103], v[162:163], off offset:528
	v_or_b32_e32 v104, 32, v146
	v_ashrrev_i32_e32 v105, 31, v104
	v_lshlrev_b64 v[104:105], 12, v[104:105]
	v_lshl_add_u64 v[104:105], s[16:17], 0, v[104:105]
	v_lshl_add_u64 v[104:105], v[104:105], 0, v[144:145]
	s_waitcnt vmcnt(0)
	v_pk_fma_f32 v[94:95], v[94:95], v[116:117], v[102:103]
	v_pk_fma_f32 v[92:93], v[92:93], v[118:119], v[100:101]
	global_store_dwordx4 v[158:159], v[92:95], off offset:528 sc1
	global_load_dwordx4 v[92:95], v[104:105], off
	v_add_u32_e32 v100, 0x120, v146
	v_ashrrev_i32_e32 v101, 31, v100
	v_lshlrev_b64 v[100:101], 12, v[100:101]
	v_lshl_add_u64 v[100:101], s[10:11], 0, v[100:101]
	v_lshl_add_u64 v[100:101], v[100:101], 0, v[144:145]
	s_waitcnt vmcnt(0)
	v_pk_fma_f32 v[94:95], v[98:99], v[148:149], v[94:95]
	v_pk_fma_f32 v[92:93], v[96:97], v[150:151], v[92:93]
	global_store_dwordx4 v[100:101], v[92:95], off sc1
	global_load_dwordx4 v[92:95], v[104:105], off offset:16
	s_waitcnt vmcnt(0)
	v_pk_fma_f32 v[90:91], v[90:91], v[124:125], v[94:95]
	v_pk_fma_f32 v[88:89], v[88:89], v[126:127], v[92:93]
	global_store_dwordx4 v[100:101], v[88:91], off offset:16 sc1
	global_load_dwordx4 v[88:91], v[104:105], off offset:512
	s_waitcnt vmcnt(0)
	v_pk_fma_f32 v[86:87], v[86:87], v[120:121], v[90:91]
	v_pk_fma_f32 v[84:85], v[84:85], v[122:123], v[88:89]
	global_store_dwordx4 v[100:101], v[84:87], off offset:512 sc1
	global_load_dwordx4 v[84:87], v[104:105], off offset:528
	v_or_b32_e32 v88, 48, v146
	v_ashrrev_i32_e32 v89, 31, v88
	v_lshlrev_b64 v[88:89], 12, v[88:89]
	v_lshl_add_u64 v[88:89], s[16:17], 0, v[88:89]
	v_lshl_add_u64 v[88:89], v[88:89], 0, v[144:145]
	s_waitcnt vmcnt(0)
	v_pk_fma_f32 v[78:79], v[78:79], v[116:117], v[86:87]
	v_pk_fma_f32 v[76:77], v[76:77], v[118:119], v[84:85]
	global_store_dwordx4 v[100:101], v[76:79], off offset:528 sc1
	global_load_dwordx4 v[76:79], v[88:89], off
	v_add_u32_e32 v84, 0x130, v146
	v_ashrrev_i32_e32 v85, 31, v84
	v_lshlrev_b64 v[84:85], 12, v[84:85]
	v_lshl_add_u64 v[84:85], s[10:11], 0, v[84:85]
	v_lshl_add_u64 v[84:85], v[84:85], 0, v[144:145]
	s_waitcnt vmcnt(0)
	v_pk_fma_f32 v[78:79], v[82:83], v[148:149], v[78:79]
	v_pk_fma_f32 v[76:77], v[80:81], v[150:151], v[76:77]
	global_store_dwordx4 v[84:85], v[76:79], off sc1
	global_load_dwordx4 v[76:79], v[88:89], off offset:16
	s_waitcnt vmcnt(0)
	v_pk_fma_f32 v[74:75], v[74:75], v[124:125], v[78:79]
	v_pk_fma_f32 v[72:73], v[72:73], v[126:127], v[76:77]
	global_store_dwordx4 v[84:85], v[72:75], off offset:16 sc1
	global_load_dwordx4 v[72:75], v[88:89], off offset:512
	s_waitcnt vmcnt(0)
	v_pk_fma_f32 v[70:71], v[70:71], v[120:121], v[74:75]
	v_pk_fma_f32 v[68:69], v[68:69], v[122:123], v[72:73]
	global_store_dwordx4 v[84:85], v[68:71], off offset:512 sc1
	global_load_dwordx4 v[68:71], v[88:89], off offset:528
	v_add_u32_e32 v72, 0x80, v146
	v_ashrrev_i32_e32 v73, 31, v72
	v_lshlrev_b64 v[72:73], 12, v[72:73]
	v_lshl_add_u64 v[72:73], s[16:17], 0, v[72:73]
	v_lshl_add_u64 v[72:73], v[72:73], 0, v[144:145]
	s_waitcnt vmcnt(0)
	v_pk_fma_f32 v[66:67], v[66:67], v[116:117], v[70:71]
	v_pk_fma_f32 v[64:65], v[64:65], v[118:119], v[68:69]
	global_store_dwordx4 v[84:85], v[64:67], off offset:528 sc1
	global_load_dwordx4 v[64:67], v[72:73], off
	v_add_u32_e32 v68, 0x180, v146
	v_ashrrev_i32_e32 v69, 31, v68
	v_lshlrev_b64 v[68:69], 12, v[68:69]
	v_lshl_add_u64 v[68:69], s[10:11], 0, v[68:69]
	v_lshl_add_u64 v[68:69], v[68:69], 0, v[144:145]
	s_waitcnt vmcnt(0)
	v_pk_fma_f32 v[62:63], v[62:63], v[148:149], v[66:67]
	v_pk_fma_f32 v[60:61], v[60:61], v[150:151], v[64:65]
	global_store_dwordx4 v[68:69], v[60:63], off sc1
	global_load_dwordx4 v[60:63], v[72:73], off offset:16
	s_waitcnt vmcnt(0)
	v_pk_fma_f32 v[58:59], v[58:59], v[124:125], v[62:63]
	v_pk_fma_f32 v[56:57], v[56:57], v[126:127], v[60:61]
	global_store_dwordx4 v[68:69], v[56:59], off offset:16 sc1
	global_load_dwordx4 v[56:59], v[72:73], off offset:512
	s_waitcnt vmcnt(0)
	v_pk_fma_f32 v[54:55], v[54:55], v[120:121], v[58:59]
	v_pk_fma_f32 v[52:53], v[52:53], v[122:123], v[56:57]
	global_store_dwordx4 v[68:69], v[52:55], off offset:512 sc1
	global_load_dwordx4 v[52:55], v[72:73], off offset:528
	v_add_u32_e32 v56, 0x90, v146
	v_ashrrev_i32_e32 v57, 31, v56
	v_lshlrev_b64 v[56:57], 12, v[56:57]
	v_lshl_add_u64 v[56:57], s[16:17], 0, v[56:57]
	v_lshl_add_u64 v[56:57], v[56:57], 0, v[144:145]
	s_waitcnt vmcnt(0)
	v_pk_fma_f32 v[46:47], v[46:47], v[116:117], v[54:55]
	v_pk_fma_f32 v[44:45], v[44:45], v[118:119], v[52:53]
	global_store_dwordx4 v[68:69], v[44:47], off offset:528 sc1
	global_load_dwordx4 v[44:47], v[56:57], off
	v_add_u32_e32 v52, 0x190, v146
	v_ashrrev_i32_e32 v53, 31, v52
	v_lshlrev_b64 v[52:53], 12, v[52:53]
	v_lshl_add_u64 v[52:53], s[10:11], 0, v[52:53]
	v_lshl_add_u64 v[52:53], v[52:53], 0, v[144:145]
	s_waitcnt vmcnt(0)
	v_pk_fma_f32 v[46:47], v[50:51], v[148:149], v[46:47]
	v_pk_fma_f32 v[44:45], v[48:49], v[150:151], v[44:45]
	global_store_dwordx4 v[52:53], v[44:47], off sc1
	global_load_dwordx4 v[44:47], v[56:57], off offset:16
	s_waitcnt vmcnt(0)
	v_pk_fma_f32 v[42:43], v[42:43], v[124:125], v[46:47]
	v_pk_fma_f32 v[40:41], v[40:41], v[126:127], v[44:45]
	global_store_dwordx4 v[52:53], v[40:43], off offset:16 sc1
	global_load_dwordx4 v[40:43], v[56:57], off offset:512
	s_waitcnt vmcnt(0)
	v_pk_fma_f32 v[38:39], v[38:39], v[120:121], v[42:43]
	v_pk_fma_f32 v[36:37], v[36:37], v[122:123], v[40:41]
	global_store_dwordx4 v[52:53], v[36:39], off offset:512 sc1
	global_load_dwordx4 v[36:39], v[56:57], off offset:528
	v_add_u32_e32 v40, 0xa0, v146
	v_ashrrev_i32_e32 v41, 31, v40
	v_lshlrev_b64 v[40:41], 12, v[40:41]
	v_lshl_add_u64 v[40:41], s[16:17], 0, v[40:41]
	v_lshl_add_u64 v[40:41], v[40:41], 0, v[144:145]
	s_waitcnt vmcnt(0)
	v_pk_fma_f32 v[30:31], v[30:31], v[116:117], v[38:39]
	v_pk_fma_f32 v[28:29], v[28:29], v[118:119], v[36:37]
	global_store_dwordx4 v[52:53], v[28:31], off offset:528 sc1
	global_load_dwordx4 v[28:31], v[40:41], off
	v_add_u32_e32 v36, 0x1a0, v146
	v_ashrrev_i32_e32 v37, 31, v36
	v_lshlrev_b64 v[36:37], 12, v[36:37]
	v_lshl_add_u64 v[36:37], s[10:11], 0, v[36:37]
	v_lshl_add_u64 v[36:37], v[36:37], 0, v[144:145]
	s_waitcnt vmcnt(0)
	v_pk_fma_f32 v[30:31], v[34:35], v[148:149], v[30:31]
	v_pk_fma_f32 v[28:29], v[32:33], v[150:151], v[28:29]
	global_store_dwordx4 v[36:37], v[28:31], off sc1
	global_load_dwordx4 v[28:31], v[40:41], off offset:16
	s_waitcnt vmcnt(0)
	v_pk_fma_f32 v[26:27], v[26:27], v[124:125], v[30:31]
	v_pk_fma_f32 v[24:25], v[24:25], v[126:127], v[28:29]
	global_store_dwordx4 v[36:37], v[24:27], off offset:16 sc1
	global_load_dwordx4 v[24:27], v[40:41], off offset:512
	s_waitcnt vmcnt(0)
	v_pk_fma_f32 v[22:23], v[22:23], v[120:121], v[26:27]
	v_pk_fma_f32 v[20:21], v[20:21], v[122:123], v[24:25]
	global_store_dwordx4 v[36:37], v[20:23], off offset:512 sc1
	global_load_dwordx4 v[20:23], v[40:41], off offset:528
	v_add_u32_e32 v24, 0xb0, v146
	v_ashrrev_i32_e32 v25, 31, v24
	v_lshlrev_b64 v[24:25], 12, v[24:25]
	v_lshl_add_u64 v[24:25], s[16:17], 0, v[24:25]
	v_lshl_add_u64 v[24:25], v[24:25], 0, v[144:145]
	s_waitcnt vmcnt(0)
	v_pk_fma_f32 v[14:15], v[14:15], v[116:117], v[22:23]
	v_pk_fma_f32 v[12:13], v[12:13], v[118:119], v[20:21]
	global_store_dwordx4 v[36:37], v[12:15], off offset:528 sc1
	global_load_dwordx4 v[12:15], v[24:25], off
	v_add_u32_e32 v20, 0x1b0, v146
	v_ashrrev_i32_e32 v21, 31, v20
	v_lshlrev_b64 v[20:21], 12, v[20:21]
	v_lshl_add_u64 v[20:21], s[10:11], 0, v[20:21]
	v_lshl_add_u64 v[20:21], v[20:21], 0, v[144:145]
	s_waitcnt vmcnt(0)
	v_pk_fma_f32 v[14:15], v[18:19], v[148:149], v[14:15]
	v_pk_fma_f32 v[12:13], v[16:17], v[150:151], v[12:13]
	global_store_dwordx4 v[20:21], v[12:15], off sc1
	global_load_dwordx4 v[12:15], v[24:25], off offset:16
	s_waitcnt vmcnt(0)
	v_pk_fma_f32 v[10:11], v[10:11], v[124:125], v[14:15]
	v_pk_fma_f32 v[8:9], v[8:9], v[126:127], v[12:13]
	global_store_dwordx4 v[20:21], v[8:11], off offset:16 sc1
	global_load_dwordx4 v[8:11], v[24:25], off offset:512
	s_waitcnt vmcnt(0)
	v_pk_fma_f32 v[6:7], v[6:7], v[120:121], v[10:11]
	v_pk_fma_f32 v[4:5], v[4:5], v[122:123], v[8:9]
	global_store_dwordx4 v[20:21], v[4:7], off offset:512 sc1
	global_load_dwordx4 v[4:7], v[24:25], off offset:528
	s_waitcnt vmcnt(0)
	v_pk_fma_f32 v[2:3], v[2:3], v[116:117], v[6:7]
	v_pk_fma_f32 v[0:1], v[0:1], v[118:119], v[4:5]
	global_store_dwordx4 v[20:21], v[0:3], off offset:528 sc1
	s_cbranch_vccnz .LBB0_344
	s_andn2_b64 vcc, exec, s[18:19]
	s_cbranch_vccnz .LBB0_343
	s_barrier
	s_branch .LBB0_343

.LBB0_952:
	v_lshl_add_u32 v168, s28, 8, v162
	v_add_u32_e32 v170, 0x100, v168
	v_lshl_or_b32 v64, s29, 8, v164
	v_ashrrev_i32_e32 v171, 31, v170
	v_ashrrev_i32_e32 v65, 31, v64
	v_lshlrev_b64 v[170:171], 12, v[170:171]
	v_lshlrev_b64 v[160:161], 2, v[64:65]
	v_lshl_add_u64 v[170:171], s[8:9], 0, v[170:171]
	v_lshl_add_u64 v[68:69], s[14:15], 0, v[160:161]
	v_lshl_add_u64 v[178:179], v[170:171], 0, v[160:161]
	global_load_dwordx4 v[112:115], v[68:69], off offset:16
	global_load_dwordx4 v[116:119], v[68:69], off
	global_load_dwordx4 v[64:67], v[68:69], off offset:528
	s_nop 0
	global_load_dwordx4 v[68:71], v[68:69], off offset:512
	s_nop 0
	global_load_dwordx4 v[170:173], v[178:179], off offset:16
	global_load_dwordx4 v[174:177], v[178:179], off
	s_mov_b64 s[28:29], -1
	s_andn2_b64 vcc, exec, s[6:7]
	s_waitcnt vmcnt(0)
	v_pk_fma_f32 v[138:139], v[138:139], v[114:115], v[172:173]
	v_pk_fma_f32 v[142:143], v[142:143], v[118:119], v[176:177]
	v_pk_fma_f32 v[140:141], v[140:141], v[116:117], v[174:175]
	v_pk_fma_f32 v[136:137], v[136:137], v[112:113], v[170:171]
	global_store_dwordx4 v[178:179], v[140:143], off sc1
	global_store_dwordx4 v[178:179], v[136:139], off offset:16 sc1
	global_load_dwordx4 v[136:139], v[178:179], off offset:528
	s_nop 0
	global_load_dwordx4 v[140:143], v[178:179], off offset:512
	s_waitcnt vmcnt(1)
	v_pk_fma_f32 v[130:131], v[130:131], v[66:67], v[138:139]
	v_pk_fma_f32 v[128:129], v[128:129], v[64:65], v[136:137]
	global_store_dwordx4 v[178:179], v[128:131], off offset:528 sc1
	s_waitcnt vmcnt(1)
	v_pk_fma_f32 v[134:135], v[134:135], v[70:71], v[142:143]
	v_pk_fma_f32 v[132:133], v[132:133], v[68:69], v[140:141]
	v_add_u32_e32 v128, 0x110, v168
	v_ashrrev_i32_e32 v129, 31, v128
	v_lshlrev_b64 v[128:129], 12, v[128:129]
	v_lshl_add_u64 v[128:129], s[8:9], 0, v[128:129]
	global_store_dwordx4 v[178:179], v[132:135], off offset:512 sc1
	v_lshl_add_u64 v[136:137], v[128:129], 0, v[160:161]
	global_load_dwordx4 v[128:131], v[136:137], off offset:16
	global_load_dwordx4 v[132:135], v[136:137], off
	s_waitcnt vmcnt(1)
	v_pk_fma_f32 v[122:123], v[122:123], v[114:115], v[130:131]
	s_waitcnt vmcnt(0)
	v_pk_fma_f32 v[126:127], v[126:127], v[118:119], v[134:135]
	v_pk_fma_f32 v[124:125], v[124:125], v[116:117], v[132:133]
	v_pk_fma_f32 v[120:121], v[120:121], v[112:113], v[128:129]
	global_store_dwordx4 v[136:137], v[124:127], off sc1
	global_store_dwordx4 v[136:137], v[120:123], off offset:16 sc1
	global_load_dwordx4 v[120:123], v[136:137], off offset:528
	s_nop 0
	global_load_dwordx4 v[124:127], v[136:137], off offset:512
	s_waitcnt vmcnt(1)
	v_pk_fma_f32 v[106:107], v[106:107], v[66:67], v[122:123]
	v_pk_fma_f32 v[104:105], v[104:105], v[64:65], v[120:121]
	global_store_dwordx4 v[136:137], v[104:107], off offset:528 sc1
	s_waitcnt vmcnt(1)
	v_pk_fma_f32 v[110:111], v[110:111], v[70:71], v[126:127]
	v_pk_fma_f32 v[108:109], v[108:109], v[68:69], v[124:125]
	v_add_u32_e32 v104, 0x120, v168
	v_ashrrev_i32_e32 v105, 31, v104
	v_lshlrev_b64 v[104:105], 12, v[104:105]
	v_lshl_add_u64 v[104:105], s[8:9], 0, v[104:105]
	global_store_dwordx4 v[136:137], v[108:111], off offset:512 sc1
	v_lshl_add_u64 v[120:121], v[104:105], 0, v[160:161]
	global_load_dwordx4 v[104:107], v[120:121], off offset:16
	global_load_dwordx4 v[108:111], v[120:121], off
	s_waitcnt vmcnt(1)
	v_pk_fma_f32 v[98:99], v[98:99], v[114:115], v[106:107]
	s_waitcnt vmcnt(0)
	v_pk_fma_f32 v[102:103], v[102:103], v[118:119], v[110:111]
	v_pk_fma_f32 v[100:101], v[100:101], v[116:117], v[108:109]
	v_pk_fma_f32 v[96:97], v[96:97], v[112:113], v[104:105]
	global_store_dwordx4 v[120:121], v[100:103], off sc1
	global_store_dwordx4 v[120:121], v[96:99], off offset:16 sc1
	global_load_dwordx4 v[96:99], v[120:121], off offset:528
	s_nop 0
	global_load_dwordx4 v[100:103], v[120:121], off offset:512
	s_waitcnt vmcnt(1)
	v_pk_fma_f32 v[90:91], v[90:91], v[66:67], v[98:99]
	v_pk_fma_f32 v[88:89], v[88:89], v[64:65], v[96:97]
	global_store_dwordx4 v[120:121], v[88:91], off offset:528 sc1
	s_waitcnt vmcnt(1)
	v_pk_fma_f32 v[94:95], v[94:95], v[70:71], v[102:103]
	v_pk_fma_f32 v[92:93], v[92:93], v[68:69], v[100:101]
	v_add_u32_e32 v88, 0x130, v168
	v_ashrrev_i32_e32 v89, 31, v88
	v_lshlrev_b64 v[88:89], 12, v[88:89]
	v_lshl_add_u64 v[88:89], s[8:9], 0, v[88:89]
	global_store_dwordx4 v[120:121], v[92:95], off offset:512 sc1
	v_lshl_add_u64 v[96:97], v[88:89], 0, v[160:161]
	global_load_dwordx4 v[88:91], v[96:97], off offset:16
	global_load_dwordx4 v[92:95], v[96:97], off
	s_waitcnt vmcnt(1)
	v_pk_fma_f32 v[82:83], v[82:83], v[114:115], v[90:91]
	s_waitcnt vmcnt(0)
	v_pk_fma_f32 v[86:87], v[86:87], v[118:119], v[94:95]
	v_pk_fma_f32 v[84:85], v[84:85], v[116:117], v[92:93]
	v_pk_fma_f32 v[80:81], v[80:81], v[112:113], v[88:89]
	global_store_dwordx4 v[96:97], v[84:87], off sc1
	global_store_dwordx4 v[96:97], v[80:83], off offset:16 sc1
	global_load_dwordx4 v[80:83], v[96:97], off offset:528
	s_nop 0
	global_load_dwordx4 v[84:87], v[96:97], off offset:512
	s_waitcnt vmcnt(1)
	v_pk_fma_f32 v[74:75], v[74:75], v[66:67], v[82:83]
	v_pk_fma_f32 v[72:73], v[72:73], v[64:65], v[80:81]
	global_store_dwordx4 v[96:97], v[72:75], off offset:528 sc1
	s_waitcnt vmcnt(1)
	v_pk_fma_f32 v[78:79], v[78:79], v[70:71], v[86:87]
	v_pk_fma_f32 v[76:77], v[76:77], v[68:69], v[84:85]
	v_add_u32_e32 v72, 0x180, v168
	v_ashrrev_i32_e32 v73, 31, v72
	v_lshlrev_b64 v[72:73], 12, v[72:73]
	v_lshl_add_u64 v[72:73], s[8:9], 0, v[72:73]
	global_store_dwordx4 v[96:97], v[76:79], off offset:512 sc1
	v_lshl_add_u64 v[80:81], v[72:73], 0, v[160:161]
	global_load_dwordx4 v[72:75], v[80:81], off offset:16
	global_load_dwordx4 v[76:79], v[80:81], off
	s_waitcnt vmcnt(1)
	v_pk_fma_f32 v[58:59], v[58:59], v[114:115], v[74:75]
	s_waitcnt vmcnt(0)
	v_pk_fma_f32 v[62:63], v[62:63], v[118:119], v[78:79]
	v_pk_fma_f32 v[60:61], v[60:61], v[116:117], v[76:77]
	v_pk_fma_f32 v[56:57], v[56:57], v[112:113], v[72:73]
	global_store_dwordx4 v[80:81], v[60:63], off sc1
	global_store_dwordx4 v[80:81], v[56:59], off offset:16 sc1
	global_load_dwordx4 v[56:59], v[80:81], off offset:528
	s_nop 0
	global_load_dwordx4 v[60:63], v[80:81], off offset:512
	s_waitcnt vmcnt(1)
	v_pk_fma_f32 v[50:51], v[50:51], v[66:67], v[58:59]
	v_pk_fma_f32 v[48:49], v[48:49], v[64:65], v[56:57]
	global_store_dwordx4 v[80:81], v[48:51], off offset:528 sc1
	s_waitcnt vmcnt(1)
	v_pk_fma_f32 v[54:55], v[54:55], v[70:71], v[62:63]
	v_pk_fma_f32 v[52:53], v[52:53], v[68:69], v[60:61]
	v_add_u32_e32 v48, 0x190, v168
	v_ashrrev_i32_e32 v49, 31, v48
	v_lshlrev_b64 v[48:49], 12, v[48:49]
	v_lshl_add_u64 v[48:49], s[8:9], 0, v[48:49]
	global_store_dwordx4 v[80:81], v[52:55], off offset:512 sc1
	v_lshl_add_u64 v[56:57], v[48:49], 0, v[160:161]
	global_load_dwordx4 v[48:51], v[56:57], off offset:16
	global_load_dwordx4 v[52:55], v[56:57], off
	s_waitcnt vmcnt(1)
	v_pk_fma_f32 v[42:43], v[42:43], v[114:115], v[50:51]
	s_waitcnt vmcnt(0)
	v_pk_fma_f32 v[46:47], v[46:47], v[118:119], v[54:55]
	v_pk_fma_f32 v[44:45], v[44:45], v[116:117], v[52:53]
	v_pk_fma_f32 v[40:41], v[40:41], v[112:113], v[48:49]
	global_store_dwordx4 v[56:57], v[44:47], off sc1
	global_store_dwordx4 v[56:57], v[40:43], off offset:16 sc1
	global_load_dwordx4 v[40:43], v[56:57], off offset:528
	s_nop 0
	global_load_dwordx4 v[44:47], v[56:57], off offset:512
	s_waitcnt vmcnt(1)
	v_pk_fma_f32 v[34:35], v[34:35], v[66:67], v[42:43]
	v_pk_fma_f32 v[32:33], v[32:33], v[64:65], v[40:41]
	global_store_dwordx4 v[56:57], v[32:35], off offset:528 sc1
	s_waitcnt vmcnt(1)
	v_pk_fma_f32 v[38:39], v[38:39], v[70:71], v[46:47]
	v_pk_fma_f32 v[36:37], v[36:37], v[68:69], v[44:45]
	v_add_u32_e32 v32, 0x1a0, v168
	v_ashrrev_i32_e32 v33, 31, v32
	v_lshlrev_b64 v[32:33], 12, v[32:33]
	v_lshl_add_u64 v[32:33], s[8:9], 0, v[32:33]
	global_store_dwordx4 v[56:57], v[36:39], off offset:512 sc1
	v_lshl_add_u64 v[40:41], v[32:33], 0, v[160:161]
	global_load_dwordx4 v[32:35], v[40:41], off offset:16
	global_load_dwordx4 v[36:39], v[40:41], off
	s_waitcnt vmcnt(1)
	v_pk_fma_f32 v[26:27], v[26:27], v[114:115], v[34:35]
	s_waitcnt vmcnt(0)
	v_pk_fma_f32 v[30:31], v[30:31], v[118:119], v[38:39]
	v_pk_fma_f32 v[28:29], v[28:29], v[116:117], v[36:37]
	v_pk_fma_f32 v[24:25], v[24:25], v[112:113], v[32:33]
	global_store_dwordx4 v[40:41], v[28:31], off sc1
	global_store_dwordx4 v[40:41], v[24:27], off offset:16 sc1
	global_load_dwordx4 v[24:27], v[40:41], off offset:528
	s_nop 0
	global_load_dwordx4 v[28:31], v[40:41], off offset:512
	s_waitcnt vmcnt(1)
	v_pk_fma_f32 v[18:19], v[18:19], v[66:67], v[26:27]
	v_pk_fma_f32 v[16:17], v[16:17], v[64:65], v[24:25]
	global_store_dwordx4 v[40:41], v[16:19], off offset:528 sc1
	s_waitcnt vmcnt(1)
	v_pk_fma_f32 v[22:23], v[22:23], v[70:71], v[30:31]
	v_pk_fma_f32 v[20:21], v[20:21], v[68:69], v[28:29]
	v_add_u32_e32 v16, 0x1b0, v168
	v_ashrrev_i32_e32 v17, 31, v16
	v_lshlrev_b64 v[16:17], 12, v[16:17]
	v_lshl_add_u64 v[16:17], s[8:9], 0, v[16:17]
	global_store_dwordx4 v[40:41], v[20:23], off offset:512 sc1
	v_lshl_add_u64 v[16:17], v[16:17], 0, v[160:161]
	global_load_dwordx4 v[18:21], v[16:17], off offset:16
	global_load_dwordx4 v[22:25], v[16:17], off
	s_waitcnt vmcnt(1)
	v_pk_fma_f32 v[10:11], v[10:11], v[114:115], v[20:21]
	s_waitcnt vmcnt(0)
	v_pk_fma_f32 v[14:15], v[14:15], v[118:119], v[24:25]
	v_pk_fma_f32 v[12:13], v[12:13], v[116:117], v[22:23]
	v_pk_fma_f32 v[8:9], v[8:9], v[112:113], v[18:19]
	global_store_dwordx4 v[16:17], v[12:15], off sc1
	global_store_dwordx4 v[16:17], v[8:11], off offset:16 sc1
	global_load_dwordx4 v[8:11], v[16:17], off offset:528
	s_nop 0
	global_load_dwordx4 v[12:15], v[16:17], off offset:512
	s_waitcnt vmcnt(1)
	v_pk_fma_f32 v[2:3], v[2:3], v[66:67], v[10:11]
	s_waitcnt vmcnt(0)
	v_pk_fma_f32 v[6:7], v[6:7], v[70:71], v[14:15]
	v_pk_fma_f32 v[4:5], v[4:5], v[68:69], v[12:13]
	v_pk_fma_f32 v[0:1], v[0:1], v[64:65], v[8:9]
	global_store_dwordx4 v[16:17], v[4:7], off offset:512 sc1
	global_store_dwordx4 v[16:17], v[0:3], off offset:528 sc1
	s_cbranch_vccnz .LBB0_945
	s_andn2_b64 vcc, exec, s[12:13]
	s_cbranch_vccnz .LBB0_944
	s_barrier
	s_branch .LBB0_944

.LBB0_1165:
	v_lshl_or_b32 v144, s52, 8, v164
	v_ashrrev_i32_e32 v145, 31, v144
	v_lshlrev_b64 v[152:153], 2, v[144:145]
	v_lshl_add_u64 v[172:173], s[16:17], 0, v[152:153]
	global_load_dwordx4 v[144:147], v[172:173], off offset:16
	global_load_dwordx4 v[148:151], v[172:173], off
	s_mov_b64 s[24:25], -1
	s_and_b64 vcc, exec, s[6:7]
	s_waitcnt vmcnt(0)
	v_pk_mul_f32 v[154:155], v[146:147], 0.5 op_sel_hi:[1,0]
	v_pk_mul_f32 v[156:157], v[144:145], 0.5 op_sel_hi:[1,0]
	global_load_dwordx4 v[168:171], v[172:173], off offset:528
	global_load_dwordx4 v[144:147], v[172:173], off offset:512
	v_pk_mul_f32 v[160:161], v[148:149], 0.5 op_sel_hi:[1,0]
	v_pk_mul_f32 v[158:159], v[150:151], 0.5 op_sel_hi:[1,0]
	s_waitcnt vmcnt(0)
	v_pk_mul_f32 v[148:149], v[146:147], 0.5 op_sel_hi:[1,0]
	v_pk_mul_f32 v[146:147], v[168:169], 0.5 op_sel_hi:[1,0]
	v_lshl_add_u32 v168, s51, 8, v162
	v_pk_mul_f32 v[150:151], v[144:145], 0.5 op_sel_hi:[1,0]
	v_pk_mul_f32 v[144:145], v[170:171], 0.5 op_sel_hi:[1,0]
	v_add_u32_e32 v170, 0x100, v168
	v_ashrrev_i32_e32 v171, 31, v170
	v_lshlrev_b64 v[170:171], 12, v[170:171]
	v_lshl_add_u64 v[170:171], s[10:11], 0, v[170:171]
	v_lshl_add_u64 v[178:179], v[170:171], 0, v[152:153]
	global_load_dwordx4 v[170:173], v[178:179], off offset:16
	global_load_dwordx4 v[174:177], v[178:179], off
	s_waitcnt vmcnt(1)
	v_pk_fma_f32 v[122:123], v[122:123], v[154:155], v[172:173]
	s_waitcnt vmcnt(0)
	v_pk_fma_f32 v[126:127], v[126:127], v[158:159], v[176:177]
	v_pk_fma_f32 v[124:125], v[124:125], v[160:161], v[174:175]
	v_pk_fma_f32 v[120:121], v[120:121], v[156:157], v[170:171]
	global_store_dwordx4 v[178:179], v[124:127], off sc1
	global_store_dwordx4 v[178:179], v[120:123], off offset:16 sc1
	global_load_dwordx4 v[120:123], v[178:179], off offset:528
	s_nop 0
	global_load_dwordx4 v[124:127], v[178:179], off offset:512
	s_waitcnt vmcnt(1)
	v_pk_fma_f32 v[114:115], v[114:115], v[144:145], v[122:123]
	v_pk_fma_f32 v[112:113], v[112:113], v[146:147], v[120:121]
	global_store_dwordx4 v[178:179], v[112:115], off offset:528 sc1
	s_waitcnt vmcnt(1)
	v_pk_fma_f32 v[118:119], v[118:119], v[148:149], v[126:127]
	v_pk_fma_f32 v[116:117], v[116:117], v[150:151], v[124:125]
	v_add_u32_e32 v112, 0x110, v168
	v_ashrrev_i32_e32 v113, 31, v112
	v_lshlrev_b64 v[112:113], 12, v[112:113]
	v_lshl_add_u64 v[112:113], s[10:11], 0, v[112:113]
	global_store_dwordx4 v[178:179], v[116:119], off offset:512 sc1
	v_lshl_add_u64 v[120:121], v[112:113], 0, v[152:153]
	global_load_dwordx4 v[112:115], v[120:121], off offset:16
	global_load_dwordx4 v[116:119], v[120:121], off
	s_waitcnt vmcnt(1)
	v_pk_fma_f32 v[106:107], v[106:107], v[154:155], v[114:115]
	s_waitcnt vmcnt(0)
	v_pk_fma_f32 v[110:111], v[110:111], v[158:159], v[118:119]
	v_pk_fma_f32 v[108:109], v[108:109], v[160:161], v[116:117]
	v_pk_fma_f32 v[104:105], v[104:105], v[156:157], v[112:113]
	global_store_dwordx4 v[120:121], v[108:111], off sc1
	global_store_dwordx4 v[120:121], v[104:107], off offset:16 sc1
	global_load_dwordx4 v[104:107], v[120:121], off offset:528
	s_nop 0
	global_load_dwordx4 v[108:111], v[120:121], off offset:512
	s_waitcnt vmcnt(1)
	v_pk_fma_f32 v[98:99], v[98:99], v[144:145], v[106:107]
	v_pk_fma_f32 v[96:97], v[96:97], v[146:147], v[104:105]
	global_store_dwordx4 v[120:121], v[96:99], off offset:528 sc1
	s_waitcnt vmcnt(1)
	v_pk_fma_f32 v[102:103], v[102:103], v[148:149], v[110:111]
	v_pk_fma_f32 v[100:101], v[100:101], v[150:151], v[108:109]
	v_add_u32_e32 v96, 0x120, v168
	v_ashrrev_i32_e32 v97, 31, v96
	v_lshlrev_b64 v[96:97], 12, v[96:97]
	v_lshl_add_u64 v[96:97], s[10:11], 0, v[96:97]
	global_store_dwordx4 v[120:121], v[100:103], off offset:512 sc1
	v_lshl_add_u64 v[104:105], v[96:97], 0, v[152:153]
	global_load_dwordx4 v[96:99], v[104:105], off offset:16
	global_load_dwordx4 v[100:103], v[104:105], off
	s_waitcnt vmcnt(1)
	v_pk_fma_f32 v[90:91], v[90:91], v[154:155], v[98:99]
	s_waitcnt vmcnt(0)
	v_pk_fma_f32 v[94:95], v[94:95], v[158:159], v[102:103]
	v_pk_fma_f32 v[92:93], v[92:93], v[160:161], v[100:101]
	v_pk_fma_f32 v[88:89], v[88:89], v[156:157], v[96:97]
	global_store_dwordx4 v[104:105], v[92:95], off sc1
	global_store_dwordx4 v[104:105], v[88:91], off offset:16 sc1
	global_load_dwordx4 v[88:91], v[104:105], off offset:528
	s_nop 0
	global_load_dwordx4 v[92:95], v[104:105], off offset:512
	s_waitcnt vmcnt(1)
	v_pk_fma_f32 v[82:83], v[82:83], v[144:145], v[90:91]
	v_pk_fma_f32 v[80:81], v[80:81], v[146:147], v[88:89]
	global_store_dwordx4 v[104:105], v[80:83], off offset:528 sc1
	s_waitcnt vmcnt(1)
	v_pk_fma_f32 v[86:87], v[86:87], v[148:149], v[94:95]
	v_pk_fma_f32 v[84:85], v[84:85], v[150:151], v[92:93]
	v_add_u32_e32 v80, 0x130, v168
	v_ashrrev_i32_e32 v81, 31, v80
	v_lshlrev_b64 v[80:81], 12, v[80:81]
	v_lshl_add_u64 v[80:81], s[10:11], 0, v[80:81]
	global_store_dwordx4 v[104:105], v[84:87], off offset:512 sc1
	v_lshl_add_u64 v[88:89], v[80:81], 0, v[152:153]
	global_load_dwordx4 v[80:83], v[88:89], off offset:16
	global_load_dwordx4 v[84:87], v[88:89], off
	s_waitcnt vmcnt(1)
	v_pk_fma_f32 v[74:75], v[74:75], v[154:155], v[82:83]
	s_waitcnt vmcnt(0)
	v_pk_fma_f32 v[78:79], v[78:79], v[158:159], v[86:87]
	v_pk_fma_f32 v[76:77], v[76:77], v[160:161], v[84:85]
	v_pk_fma_f32 v[72:73], v[72:73], v[156:157], v[80:81]
	global_store_dwordx4 v[88:89], v[76:79], off sc1
	global_store_dwordx4 v[88:89], v[72:75], off offset:16 sc1
	global_load_dwordx4 v[72:75], v[88:89], off offset:528
	s_nop 0
	global_load_dwordx4 v[76:79], v[88:89], off offset:512
	s_waitcnt vmcnt(1)
	v_pk_fma_f32 v[66:67], v[66:67], v[144:145], v[74:75]
	v_pk_fma_f32 v[64:65], v[64:65], v[146:147], v[72:73]
	global_store_dwordx4 v[88:89], v[64:67], off offset:528 sc1
	s_waitcnt vmcnt(1)
	v_pk_fma_f32 v[70:71], v[70:71], v[148:149], v[78:79]
	v_pk_fma_f32 v[68:69], v[68:69], v[150:151], v[76:77]
	v_add_u32_e32 v64, 0x180, v168
	v_ashrrev_i32_e32 v65, 31, v64
	v_lshlrev_b64 v[64:65], 12, v[64:65]
	v_lshl_add_u64 v[64:65], s[10:11], 0, v[64:65]
	global_store_dwordx4 v[88:89], v[68:71], off offset:512 sc1
	v_lshl_add_u64 v[72:73], v[64:65], 0, v[152:153]
	global_load_dwordx4 v[64:67], v[72:73], off offset:16
	global_load_dwordx4 v[68:71], v[72:73], off
	s_waitcnt vmcnt(1)
	v_pk_fma_f32 v[58:59], v[58:59], v[154:155], v[66:67]
	s_waitcnt vmcnt(0)
	v_pk_fma_f32 v[62:63], v[62:63], v[158:159], v[70:71]
	v_pk_fma_f32 v[60:61], v[60:61], v[160:161], v[68:69]
	v_pk_fma_f32 v[56:57], v[56:57], v[156:157], v[64:65]
	global_store_dwordx4 v[72:73], v[60:63], off sc1
	global_store_dwordx4 v[72:73], v[56:59], off offset:16 sc1
	global_load_dwordx4 v[56:59], v[72:73], off offset:528
	s_nop 0
	global_load_dwordx4 v[60:63], v[72:73], off offset:512
	s_waitcnt vmcnt(1)
	v_pk_fma_f32 v[50:51], v[50:51], v[144:145], v[58:59]
	v_pk_fma_f32 v[48:49], v[48:49], v[146:147], v[56:57]
	global_store_dwordx4 v[72:73], v[48:51], off offset:528 sc1
	s_waitcnt vmcnt(1)
	v_pk_fma_f32 v[54:55], v[54:55], v[148:149], v[62:63]
	v_pk_fma_f32 v[52:53], v[52:53], v[150:151], v[60:61]
	v_add_u32_e32 v48, 0x190, v168
	v_ashrrev_i32_e32 v49, 31, v48
	v_lshlrev_b64 v[48:49], 12, v[48:49]
	v_lshl_add_u64 v[48:49], s[10:11], 0, v[48:49]
	global_store_dwordx4 v[72:73], v[52:55], off offset:512 sc1
	v_lshl_add_u64 v[56:57], v[48:49], 0, v[152:153]
	global_load_dwordx4 v[48:51], v[56:57], off offset:16
	global_load_dwordx4 v[52:55], v[56:57], off
	s_waitcnt vmcnt(1)
	v_pk_fma_f32 v[42:43], v[42:43], v[154:155], v[50:51]
	s_waitcnt vmcnt(0)
	v_pk_fma_f32 v[46:47], v[46:47], v[158:159], v[54:55]
	v_pk_fma_f32 v[44:45], v[44:45], v[160:161], v[52:53]
	v_pk_fma_f32 v[40:41], v[40:41], v[156:157], v[48:49]
	global_store_dwordx4 v[56:57], v[44:47], off sc1
	global_store_dwordx4 v[56:57], v[40:43], off offset:16 sc1
	global_load_dwordx4 v[40:43], v[56:57], off offset:528
	s_nop 0
	global_load_dwordx4 v[44:47], v[56:57], off offset:512
	s_waitcnt vmcnt(1)
	v_pk_fma_f32 v[34:35], v[34:35], v[144:145], v[42:43]
	v_pk_fma_f32 v[32:33], v[32:33], v[146:147], v[40:41]
	global_store_dwordx4 v[56:57], v[32:35], off offset:528 sc1
	s_waitcnt vmcnt(1)
	v_pk_fma_f32 v[38:39], v[38:39], v[148:149], v[46:47]
	v_pk_fma_f32 v[36:37], v[36:37], v[150:151], v[44:45]
	v_add_u32_e32 v32, 0x1a0, v168
	v_ashrrev_i32_e32 v33, 31, v32
	v_lshlrev_b64 v[32:33], 12, v[32:33]
	v_lshl_add_u64 v[32:33], s[10:11], 0, v[32:33]
	global_store_dwordx4 v[56:57], v[36:39], off offset:512 sc1
	v_lshl_add_u64 v[40:41], v[32:33], 0, v[152:153]
	global_load_dwordx4 v[32:35], v[40:41], off offset:16
	global_load_dwordx4 v[36:39], v[40:41], off
	s_waitcnt vmcnt(1)
	v_pk_fma_f32 v[26:27], v[26:27], v[154:155], v[34:35]
	s_waitcnt vmcnt(0)
	v_pk_fma_f32 v[30:31], v[30:31], v[158:159], v[38:39]
	v_pk_fma_f32 v[28:29], v[28:29], v[160:161], v[36:37]
	v_pk_fma_f32 v[24:25], v[24:25], v[156:157], v[32:33]
	global_store_dwordx4 v[40:41], v[28:31], off sc1
	global_store_dwordx4 v[40:41], v[24:27], off offset:16 sc1
	global_load_dwordx4 v[24:27], v[40:41], off offset:528
	s_nop 0
	global_load_dwordx4 v[28:31], v[40:41], off offset:512
	s_waitcnt vmcnt(1)
	v_pk_fma_f32 v[18:19], v[18:19], v[144:145], v[26:27]
	v_pk_fma_f32 v[16:17], v[16:17], v[146:147], v[24:25]
	global_store_dwordx4 v[40:41], v[16:19], off offset:528 sc1
	s_waitcnt vmcnt(1)
	v_pk_fma_f32 v[22:23], v[22:23], v[148:149], v[30:31]
	v_pk_fma_f32 v[20:21], v[20:21], v[150:151], v[28:29]
	v_add_u32_e32 v16, 0x1b0, v168
	v_ashrrev_i32_e32 v17, 31, v16
	v_lshlrev_b64 v[16:17], 12, v[16:17]
	v_lshl_add_u64 v[16:17], s[10:11], 0, v[16:17]
	global_store_dwordx4 v[40:41], v[20:23], off offset:512 sc1
	v_lshl_add_u64 v[16:17], v[16:17], 0, v[152:153]
	global_load_dwordx4 v[18:21], v[16:17], off offset:16
	global_load_dwordx4 v[22:25], v[16:17], off
	s_waitcnt vmcnt(1)
	v_pk_fma_f32 v[10:11], v[10:11], v[154:155], v[20:21]
	s_waitcnt vmcnt(0)
	v_pk_fma_f32 v[14:15], v[14:15], v[158:159], v[24:25]
	v_pk_fma_f32 v[12:13], v[12:13], v[160:161], v[22:23]
	v_pk_fma_f32 v[8:9], v[8:9], v[156:157], v[18:19]
	global_store_dwordx4 v[16:17], v[12:15], off sc1
	global_store_dwordx4 v[16:17], v[8:11], off offset:16 sc1
	global_load_dwordx4 v[8:11], v[16:17], off offset:528
	s_nop 0
	global_load_dwordx4 v[12:15], v[16:17], off offset:512
	s_waitcnt vmcnt(1)
	v_pk_fma_f32 v[2:3], v[2:3], v[144:145], v[10:11]
	s_waitcnt vmcnt(0)
	v_pk_fma_f32 v[6:7], v[6:7], v[148:149], v[14:15]
	v_pk_fma_f32 v[4:5], v[4:5], v[150:151], v[12:13]
	v_pk_fma_f32 v[0:1], v[0:1], v[146:147], v[8:9]
	global_store_dwordx4 v[16:17], v[4:7], off offset:512 sc1
	global_store_dwordx4 v[16:17], v[0:3], off offset:528 sc1
	s_cbranch_vccnz .LBB0_1154
	s_andn2_b64 vcc, exec, s[14:15]
	s_cbranch_vccnz .LBB0_1153
	s_barrier
	s_branch .LBB0_1153

.LBB0_1579:
	v_lshl_add_u32 v160, s28, 8, v154
	v_add_u32_e32 v162, 0x100, v160
	v_lshl_or_b32 v64, s29, 8, v156
	v_ashrrev_i32_e32 v163, 31, v162
	v_ashrrev_i32_e32 v65, 31, v64
	v_lshlrev_b64 v[162:163], 12, v[162:163]
	v_lshlrev_b64 v[152:153], 2, v[64:65]
	v_lshl_add_u64 v[162:163], s[6:7], 0, v[162:163]
	v_lshl_add_u64 v[68:69], s[12:13], 0, v[152:153]
	v_lshl_add_u64 v[170:171], v[162:163], 0, v[152:153]
	global_load_dwordx4 v[112:115], v[68:69], off offset:16
	global_load_dwordx4 v[116:119], v[68:69], off
	global_load_dwordx4 v[64:67], v[68:69], off offset:528
	s_nop 0
	global_load_dwordx4 v[68:71], v[68:69], off offset:512
	s_nop 0
	global_load_dwordx4 v[162:165], v[170:171], off offset:16
	global_load_dwordx4 v[166:169], v[170:171], off
	s_mov_b64 s[28:29], -1
	s_andn2_b64 vcc, exec, s[22:23]
	s_waitcnt vmcnt(0)
	v_pk_fma_f32 v[138:139], v[138:139], v[114:115], v[164:165]
	v_pk_fma_f32 v[142:143], v[142:143], v[118:119], v[168:169]
	v_pk_fma_f32 v[140:141], v[140:141], v[116:117], v[166:167]
	v_pk_fma_f32 v[136:137], v[136:137], v[112:113], v[162:163]
	global_store_dwordx4 v[170:171], v[140:143], off sc1
	global_store_dwordx4 v[170:171], v[136:139], off offset:16 sc1
	global_load_dwordx4 v[136:139], v[170:171], off offset:528
	s_nop 0
	global_load_dwordx4 v[140:143], v[170:171], off offset:512
	s_waitcnt vmcnt(1)
	v_pk_fma_f32 v[130:131], v[130:131], v[66:67], v[138:139]
	v_pk_fma_f32 v[128:129], v[128:129], v[64:65], v[136:137]
	global_store_dwordx4 v[170:171], v[128:131], off offset:528 sc1
	s_waitcnt vmcnt(1)
	v_pk_fma_f32 v[134:135], v[134:135], v[70:71], v[142:143]
	v_pk_fma_f32 v[132:133], v[132:133], v[68:69], v[140:141]
	v_add_u32_e32 v128, 0x110, v160
	v_ashrrev_i32_e32 v129, 31, v128
	v_lshlrev_b64 v[128:129], 12, v[128:129]
	v_lshl_add_u64 v[128:129], s[6:7], 0, v[128:129]
	global_store_dwordx4 v[170:171], v[132:135], off offset:512 sc1
	v_lshl_add_u64 v[136:137], v[128:129], 0, v[152:153]
	global_load_dwordx4 v[128:131], v[136:137], off offset:16
	global_load_dwordx4 v[132:135], v[136:137], off
	s_waitcnt vmcnt(1)
	v_pk_fma_f32 v[122:123], v[122:123], v[114:115], v[130:131]
	s_waitcnt vmcnt(0)
	v_pk_fma_f32 v[126:127], v[126:127], v[118:119], v[134:135]
	v_pk_fma_f32 v[124:125], v[124:125], v[116:117], v[132:133]
	v_pk_fma_f32 v[120:121], v[120:121], v[112:113], v[128:129]
	global_store_dwordx4 v[136:137], v[124:127], off sc1
	global_store_dwordx4 v[136:137], v[120:123], off offset:16 sc1
	global_load_dwordx4 v[120:123], v[136:137], off offset:528
	s_nop 0
	global_load_dwordx4 v[124:127], v[136:137], off offset:512
	s_waitcnt vmcnt(1)
	v_pk_fma_f32 v[106:107], v[106:107], v[66:67], v[122:123]
	v_pk_fma_f32 v[104:105], v[104:105], v[64:65], v[120:121]
	global_store_dwordx4 v[136:137], v[104:107], off offset:528 sc1
	s_waitcnt vmcnt(1)
	v_pk_fma_f32 v[110:111], v[110:111], v[70:71], v[126:127]
	v_pk_fma_f32 v[108:109], v[108:109], v[68:69], v[124:125]
	v_add_u32_e32 v104, 0x120, v160
	v_ashrrev_i32_e32 v105, 31, v104
	v_lshlrev_b64 v[104:105], 12, v[104:105]
	v_lshl_add_u64 v[104:105], s[6:7], 0, v[104:105]
	global_store_dwordx4 v[136:137], v[108:111], off offset:512 sc1
	v_lshl_add_u64 v[120:121], v[104:105], 0, v[152:153]
	global_load_dwordx4 v[104:107], v[120:121], off offset:16
	global_load_dwordx4 v[108:111], v[120:121], off
	s_waitcnt vmcnt(1)
	v_pk_fma_f32 v[98:99], v[98:99], v[114:115], v[106:107]
	s_waitcnt vmcnt(0)
	v_pk_fma_f32 v[102:103], v[102:103], v[118:119], v[110:111]
	v_pk_fma_f32 v[100:101], v[100:101], v[116:117], v[108:109]
	v_pk_fma_f32 v[96:97], v[96:97], v[112:113], v[104:105]
	global_store_dwordx4 v[120:121], v[100:103], off sc1
	global_store_dwordx4 v[120:121], v[96:99], off offset:16 sc1
	global_load_dwordx4 v[96:99], v[120:121], off offset:528
	s_nop 0
	global_load_dwordx4 v[100:103], v[120:121], off offset:512
	s_waitcnt vmcnt(1)
	v_pk_fma_f32 v[90:91], v[90:91], v[66:67], v[98:99]
	v_pk_fma_f32 v[88:89], v[88:89], v[64:65], v[96:97]
	global_store_dwordx4 v[120:121], v[88:91], off offset:528 sc1
	s_waitcnt vmcnt(1)
	v_pk_fma_f32 v[94:95], v[94:95], v[70:71], v[102:103]
	v_pk_fma_f32 v[92:93], v[92:93], v[68:69], v[100:101]
	v_add_u32_e32 v88, 0x130, v160
	v_ashrrev_i32_e32 v89, 31, v88
	v_lshlrev_b64 v[88:89], 12, v[88:89]
	v_lshl_add_u64 v[88:89], s[6:7], 0, v[88:89]
	global_store_dwordx4 v[120:121], v[92:95], off offset:512 sc1
	v_lshl_add_u64 v[96:97], v[88:89], 0, v[152:153]
	global_load_dwordx4 v[88:91], v[96:97], off offset:16
	global_load_dwordx4 v[92:95], v[96:97], off
	s_waitcnt vmcnt(1)
	v_pk_fma_f32 v[82:83], v[82:83], v[114:115], v[90:91]
	s_waitcnt vmcnt(0)
	v_pk_fma_f32 v[86:87], v[86:87], v[118:119], v[94:95]
	v_pk_fma_f32 v[84:85], v[84:85], v[116:117], v[92:93]
	v_pk_fma_f32 v[80:81], v[80:81], v[112:113], v[88:89]
	global_store_dwordx4 v[96:97], v[84:87], off sc1
	global_store_dwordx4 v[96:97], v[80:83], off offset:16 sc1
	global_load_dwordx4 v[80:83], v[96:97], off offset:528
	s_nop 0
	global_load_dwordx4 v[84:87], v[96:97], off offset:512
	s_waitcnt vmcnt(1)
	v_pk_fma_f32 v[74:75], v[74:75], v[66:67], v[82:83]
	v_pk_fma_f32 v[72:73], v[72:73], v[64:65], v[80:81]
	global_store_dwordx4 v[96:97], v[72:75], off offset:528 sc1
	s_waitcnt vmcnt(1)
	v_pk_fma_f32 v[78:79], v[78:79], v[70:71], v[86:87]
	v_pk_fma_f32 v[76:77], v[76:77], v[68:69], v[84:85]
	v_add_u32_e32 v72, 0x180, v160
	v_ashrrev_i32_e32 v73, 31, v72
	v_lshlrev_b64 v[72:73], 12, v[72:73]
	v_lshl_add_u64 v[72:73], s[6:7], 0, v[72:73]
	global_store_dwordx4 v[96:97], v[76:79], off offset:512 sc1
	v_lshl_add_u64 v[80:81], v[72:73], 0, v[152:153]
	global_load_dwordx4 v[72:75], v[80:81], off offset:16
	global_load_dwordx4 v[76:79], v[80:81], off
	s_waitcnt vmcnt(1)
	v_pk_fma_f32 v[58:59], v[58:59], v[114:115], v[74:75]
	s_waitcnt vmcnt(0)
	v_pk_fma_f32 v[62:63], v[62:63], v[118:119], v[78:79]
	v_pk_fma_f32 v[60:61], v[60:61], v[116:117], v[76:77]
	v_pk_fma_f32 v[56:57], v[56:57], v[112:113], v[72:73]
	global_store_dwordx4 v[80:81], v[60:63], off sc1
	global_store_dwordx4 v[80:81], v[56:59], off offset:16 sc1
	global_load_dwordx4 v[56:59], v[80:81], off offset:528
	s_nop 0
	global_load_dwordx4 v[60:63], v[80:81], off offset:512
	s_waitcnt vmcnt(1)
	v_pk_fma_f32 v[50:51], v[50:51], v[66:67], v[58:59]
	v_pk_fma_f32 v[48:49], v[48:49], v[64:65], v[56:57]
	global_store_dwordx4 v[80:81], v[48:51], off offset:528 sc1
	s_waitcnt vmcnt(1)
	v_pk_fma_f32 v[54:55], v[54:55], v[70:71], v[62:63]
	v_pk_fma_f32 v[52:53], v[52:53], v[68:69], v[60:61]
	v_add_u32_e32 v48, 0x190, v160
	v_ashrrev_i32_e32 v49, 31, v48
	v_lshlrev_b64 v[48:49], 12, v[48:49]
	v_lshl_add_u64 v[48:49], s[6:7], 0, v[48:49]
	global_store_dwordx4 v[80:81], v[52:55], off offset:512 sc1
	v_lshl_add_u64 v[56:57], v[48:49], 0, v[152:153]
	global_load_dwordx4 v[48:51], v[56:57], off offset:16
	global_load_dwordx4 v[52:55], v[56:57], off
	s_waitcnt vmcnt(1)
	v_pk_fma_f32 v[42:43], v[42:43], v[114:115], v[50:51]
	s_waitcnt vmcnt(0)
	v_pk_fma_f32 v[46:47], v[46:47], v[118:119], v[54:55]
	v_pk_fma_f32 v[44:45], v[44:45], v[116:117], v[52:53]
	v_pk_fma_f32 v[40:41], v[40:41], v[112:113], v[48:49]
	global_store_dwordx4 v[56:57], v[44:47], off sc1
	global_store_dwordx4 v[56:57], v[40:43], off offset:16 sc1
	global_load_dwordx4 v[40:43], v[56:57], off offset:528
	s_nop 0
	global_load_dwordx4 v[44:47], v[56:57], off offset:512
	s_waitcnt vmcnt(1)
	v_pk_fma_f32 v[34:35], v[34:35], v[66:67], v[42:43]
	v_pk_fma_f32 v[32:33], v[32:33], v[64:65], v[40:41]
	global_store_dwordx4 v[56:57], v[32:35], off offset:528 sc1
	s_waitcnt vmcnt(1)
	v_pk_fma_f32 v[38:39], v[38:39], v[70:71], v[46:47]
	v_pk_fma_f32 v[36:37], v[36:37], v[68:69], v[44:45]
	v_add_u32_e32 v32, 0x1a0, v160
	v_ashrrev_i32_e32 v33, 31, v32
	v_lshlrev_b64 v[32:33], 12, v[32:33]
	v_lshl_add_u64 v[32:33], s[6:7], 0, v[32:33]
	global_store_dwordx4 v[56:57], v[36:39], off offset:512 sc1
	v_lshl_add_u64 v[40:41], v[32:33], 0, v[152:153]
	global_load_dwordx4 v[32:35], v[40:41], off offset:16
	global_load_dwordx4 v[36:39], v[40:41], off
	s_waitcnt vmcnt(1)
	v_pk_fma_f32 v[26:27], v[26:27], v[114:115], v[34:35]
	s_waitcnt vmcnt(0)
	v_pk_fma_f32 v[30:31], v[30:31], v[118:119], v[38:39]
	v_pk_fma_f32 v[28:29], v[28:29], v[116:117], v[36:37]
	v_pk_fma_f32 v[24:25], v[24:25], v[112:113], v[32:33]
	global_store_dwordx4 v[40:41], v[28:31], off sc1
	global_store_dwordx4 v[40:41], v[24:27], off offset:16 sc1
	global_load_dwordx4 v[24:27], v[40:41], off offset:528
	s_nop 0
	global_load_dwordx4 v[28:31], v[40:41], off offset:512
	s_waitcnt vmcnt(1)
	v_pk_fma_f32 v[18:19], v[18:19], v[66:67], v[26:27]
	v_pk_fma_f32 v[16:17], v[16:17], v[64:65], v[24:25]
	global_store_dwordx4 v[40:41], v[16:19], off offset:528 sc1
	s_waitcnt vmcnt(1)
	v_pk_fma_f32 v[22:23], v[22:23], v[70:71], v[30:31]
	v_pk_fma_f32 v[20:21], v[20:21], v[68:69], v[28:29]
	v_add_u32_e32 v16, 0x1b0, v160
	v_ashrrev_i32_e32 v17, 31, v16
	v_lshlrev_b64 v[16:17], 12, v[16:17]
	v_lshl_add_u64 v[16:17], s[6:7], 0, v[16:17]
	global_store_dwordx4 v[40:41], v[20:23], off offset:512 sc1
	v_lshl_add_u64 v[16:17], v[16:17], 0, v[152:153]
	global_load_dwordx4 v[18:21], v[16:17], off offset:16
	global_load_dwordx4 v[22:25], v[16:17], off
	s_waitcnt vmcnt(1)
	v_pk_fma_f32 v[10:11], v[10:11], v[114:115], v[20:21]
	s_waitcnt vmcnt(0)
	v_pk_fma_f32 v[14:15], v[14:15], v[118:119], v[24:25]
	v_pk_fma_f32 v[12:13], v[12:13], v[116:117], v[22:23]
	v_pk_fma_f32 v[8:9], v[8:9], v[112:113], v[18:19]
	global_store_dwordx4 v[16:17], v[12:15], off sc1
	global_store_dwordx4 v[16:17], v[8:11], off offset:16 sc1
	global_load_dwordx4 v[8:11], v[16:17], off offset:528
	s_nop 0
	global_load_dwordx4 v[12:15], v[16:17], off offset:512
	s_waitcnt vmcnt(1)
	v_pk_fma_f32 v[2:3], v[2:3], v[66:67], v[10:11]
	s_waitcnt vmcnt(0)
	v_pk_fma_f32 v[6:7], v[6:7], v[70:71], v[14:15]
	v_pk_fma_f32 v[4:5], v[4:5], v[68:69], v[12:13]
	v_pk_fma_f32 v[0:1], v[0:1], v[64:65], v[8:9]
	global_store_dwordx4 v[16:17], v[4:7], off offset:512 sc1
	global_store_dwordx4 v[16:17], v[0:3], off offset:528 sc1
	s_cbranch_vccnz .LBB0_1572
	s_andn2_b64 vcc, exec, s[10:11]
	s_cbranch_vccnz .LBB0_1571
	s_barrier
	s_branch .LBB0_1571

.LBB0_1595:
	v_lshl_add_u32 v160, s28, 8, v154
	v_add_u32_e32 v162, 0x100, v160
	v_lshl_or_b32 v64, s29, 8, v156
	v_ashrrev_i32_e32 v163, 31, v162
	v_ashrrev_i32_e32 v65, 31, v64
	v_lshlrev_b64 v[162:163], 12, v[162:163]
	v_lshlrev_b64 v[152:153], 2, v[64:65]
	v_lshl_add_u64 v[162:163], s[6:7], 0, v[162:163]
	v_lshl_add_u64 v[68:69], s[12:13], 0, v[152:153]
	v_lshl_add_u64 v[170:171], v[162:163], 0, v[152:153]
	global_load_dwordx4 v[112:115], v[68:69], off offset:16
	global_load_dwordx4 v[116:119], v[68:69], off
	global_load_dwordx4 v[64:67], v[68:69], off offset:528
	s_nop 0
	global_load_dwordx4 v[68:71], v[68:69], off offset:512
	s_nop 0
	global_load_dwordx4 v[162:165], v[170:171], off offset:1040
	global_load_dwordx4 v[166:169], v[170:171], off offset:1024
	s_mov_b64 s[28:29], -1
	s_and_b64 vcc, s[26:27], exec
	s_waitcnt vmcnt(0)
	v_pk_fma_f32 v[138:139], v[138:139], v[114:115], v[164:165]
	v_pk_fma_f32 v[142:143], v[142:143], v[118:119], v[168:169]
	v_pk_fma_f32 v[140:141], v[140:141], v[116:117], v[166:167]
	v_pk_fma_f32 v[136:137], v[136:137], v[112:113], v[162:163]
	global_store_dwordx4 v[170:171], v[140:143], off offset:1024 sc1
	global_store_dwordx4 v[170:171], v[136:139], off offset:1040 sc1
	global_load_dwordx4 v[136:139], v[170:171], off offset:1552
	s_nop 0
	global_load_dwordx4 v[140:143], v[170:171], off offset:1536
	s_waitcnt vmcnt(1)
	v_pk_fma_f32 v[130:131], v[130:131], v[66:67], v[138:139]
	v_pk_fma_f32 v[128:129], v[128:129], v[64:65], v[136:137]
	global_store_dwordx4 v[170:171], v[128:131], off offset:1552 sc1
	s_waitcnt vmcnt(1)
	v_pk_fma_f32 v[134:135], v[134:135], v[70:71], v[142:143]
	v_pk_fma_f32 v[132:133], v[132:133], v[68:69], v[140:141]
	v_add_u32_e32 v128, 0x110, v160
	v_ashrrev_i32_e32 v129, 31, v128
	v_lshlrev_b64 v[128:129], 12, v[128:129]
	v_lshl_add_u64 v[128:129], s[6:7], 0, v[128:129]
	global_store_dwordx4 v[170:171], v[132:135], off offset:1536 sc1
	v_lshl_add_u64 v[136:137], v[128:129], 0, v[152:153]
	global_load_dwordx4 v[128:131], v[136:137], off offset:1040
	global_load_dwordx4 v[132:135], v[136:137], off offset:1024
	s_waitcnt vmcnt(1)
	v_pk_fma_f32 v[122:123], v[122:123], v[114:115], v[130:131]
	s_waitcnt vmcnt(0)
	v_pk_fma_f32 v[126:127], v[126:127], v[118:119], v[134:135]
	v_pk_fma_f32 v[124:125], v[124:125], v[116:117], v[132:133]
	v_pk_fma_f32 v[120:121], v[120:121], v[112:113], v[128:129]
	global_store_dwordx4 v[136:137], v[124:127], off offset:1024 sc1
	global_store_dwordx4 v[136:137], v[120:123], off offset:1040 sc1
	global_load_dwordx4 v[120:123], v[136:137], off offset:1552
	s_nop 0
	global_load_dwordx4 v[124:127], v[136:137], off offset:1536
	s_waitcnt vmcnt(1)
	v_pk_fma_f32 v[106:107], v[106:107], v[66:67], v[122:123]
	v_pk_fma_f32 v[104:105], v[104:105], v[64:65], v[120:121]
	global_store_dwordx4 v[136:137], v[104:107], off offset:1552 sc1
	s_waitcnt vmcnt(1)
	v_pk_fma_f32 v[110:111], v[110:111], v[70:71], v[126:127]
	v_pk_fma_f32 v[108:109], v[108:109], v[68:69], v[124:125]
	v_add_u32_e32 v104, 0x120, v160
	v_ashrrev_i32_e32 v105, 31, v104
	v_lshlrev_b64 v[104:105], 12, v[104:105]
	v_lshl_add_u64 v[104:105], s[6:7], 0, v[104:105]
	global_store_dwordx4 v[136:137], v[108:111], off offset:1536 sc1
	v_lshl_add_u64 v[120:121], v[104:105], 0, v[152:153]
	global_load_dwordx4 v[104:107], v[120:121], off offset:1040
	global_load_dwordx4 v[108:111], v[120:121], off offset:1024
	s_waitcnt vmcnt(1)
	v_pk_fma_f32 v[98:99], v[98:99], v[114:115], v[106:107]
	s_waitcnt vmcnt(0)
	v_pk_fma_f32 v[102:103], v[102:103], v[118:119], v[110:111]
	v_pk_fma_f32 v[100:101], v[100:101], v[116:117], v[108:109]
	v_pk_fma_f32 v[96:97], v[96:97], v[112:113], v[104:105]
	global_store_dwordx4 v[120:121], v[100:103], off offset:1024 sc1
	global_store_dwordx4 v[120:121], v[96:99], off offset:1040 sc1
	global_load_dwordx4 v[96:99], v[120:121], off offset:1552
	s_nop 0
	global_load_dwordx4 v[100:103], v[120:121], off offset:1536
	s_waitcnt vmcnt(1)
	v_pk_fma_f32 v[90:91], v[90:91], v[66:67], v[98:99]
	v_pk_fma_f32 v[88:89], v[88:89], v[64:65], v[96:97]
	global_store_dwordx4 v[120:121], v[88:91], off offset:1552 sc1
	s_waitcnt vmcnt(1)
	v_pk_fma_f32 v[94:95], v[94:95], v[70:71], v[102:103]
	v_pk_fma_f32 v[92:93], v[92:93], v[68:69], v[100:101]
	v_add_u32_e32 v88, 0x130, v160
	v_ashrrev_i32_e32 v89, 31, v88
	v_lshlrev_b64 v[88:89], 12, v[88:89]
	v_lshl_add_u64 v[88:89], s[6:7], 0, v[88:89]
	global_store_dwordx4 v[120:121], v[92:95], off offset:1536 sc1
	v_lshl_add_u64 v[96:97], v[88:89], 0, v[152:153]
	global_load_dwordx4 v[88:91], v[96:97], off offset:1040
	global_load_dwordx4 v[92:95], v[96:97], off offset:1024
	s_waitcnt vmcnt(1)
	v_pk_fma_f32 v[82:83], v[82:83], v[114:115], v[90:91]
	s_waitcnt vmcnt(0)
	v_pk_fma_f32 v[86:87], v[86:87], v[118:119], v[94:95]
	v_pk_fma_f32 v[84:85], v[84:85], v[116:117], v[92:93]
	v_pk_fma_f32 v[80:81], v[80:81], v[112:113], v[88:89]
	global_store_dwordx4 v[96:97], v[84:87], off offset:1024 sc1
	global_store_dwordx4 v[96:97], v[80:83], off offset:1040 sc1
	global_load_dwordx4 v[80:83], v[96:97], off offset:1552
	s_nop 0
	global_load_dwordx4 v[84:87], v[96:97], off offset:1536
	s_waitcnt vmcnt(1)
	v_pk_fma_f32 v[74:75], v[74:75], v[66:67], v[82:83]
	v_pk_fma_f32 v[72:73], v[72:73], v[64:65], v[80:81]
	global_store_dwordx4 v[96:97], v[72:75], off offset:1552 sc1
	s_waitcnt vmcnt(1)
	v_pk_fma_f32 v[78:79], v[78:79], v[70:71], v[86:87]
	v_pk_fma_f32 v[76:77], v[76:77], v[68:69], v[84:85]
	v_add_u32_e32 v72, 0x180, v160
	v_ashrrev_i32_e32 v73, 31, v72
	v_lshlrev_b64 v[72:73], 12, v[72:73]
	v_lshl_add_u64 v[72:73], s[6:7], 0, v[72:73]
	global_store_dwordx4 v[96:97], v[76:79], off offset:1536 sc1
	v_lshl_add_u64 v[80:81], v[72:73], 0, v[152:153]
	global_load_dwordx4 v[72:75], v[80:81], off offset:1040
	global_load_dwordx4 v[76:79], v[80:81], off offset:1024
	s_waitcnt vmcnt(1)
	v_pk_fma_f32 v[58:59], v[58:59], v[114:115], v[74:75]
	s_waitcnt vmcnt(0)
	v_pk_fma_f32 v[62:63], v[62:63], v[118:119], v[78:79]
	v_pk_fma_f32 v[60:61], v[60:61], v[116:117], v[76:77]
	v_pk_fma_f32 v[56:57], v[56:57], v[112:113], v[72:73]
	global_store_dwordx4 v[80:81], v[60:63], off offset:1024 sc1
	global_store_dwordx4 v[80:81], v[56:59], off offset:1040 sc1
	global_load_dwordx4 v[56:59], v[80:81], off offset:1552
	s_nop 0
	global_load_dwordx4 v[60:63], v[80:81], off offset:1536
	s_waitcnt vmcnt(1)
	v_pk_fma_f32 v[50:51], v[50:51], v[66:67], v[58:59]
	v_pk_fma_f32 v[48:49], v[48:49], v[64:65], v[56:57]
	global_store_dwordx4 v[80:81], v[48:51], off offset:1552 sc1
	s_waitcnt vmcnt(1)
	v_pk_fma_f32 v[54:55], v[54:55], v[70:71], v[62:63]
	v_pk_fma_f32 v[52:53], v[52:53], v[68:69], v[60:61]
	v_add_u32_e32 v48, 0x190, v160
	v_ashrrev_i32_e32 v49, 31, v48
	v_lshlrev_b64 v[48:49], 12, v[48:49]
	v_lshl_add_u64 v[48:49], s[6:7], 0, v[48:49]
	global_store_dwordx4 v[80:81], v[52:55], off offset:1536 sc1
	v_lshl_add_u64 v[56:57], v[48:49], 0, v[152:153]
	global_load_dwordx4 v[48:51], v[56:57], off offset:1040
	global_load_dwordx4 v[52:55], v[56:57], off offset:1024
	s_waitcnt vmcnt(1)
	v_pk_fma_f32 v[42:43], v[42:43], v[114:115], v[50:51]
	s_waitcnt vmcnt(0)
	v_pk_fma_f32 v[46:47], v[46:47], v[118:119], v[54:55]
	v_pk_fma_f32 v[44:45], v[44:45], v[116:117], v[52:53]
	v_pk_fma_f32 v[40:41], v[40:41], v[112:113], v[48:49]
	global_store_dwordx4 v[56:57], v[44:47], off offset:1024 sc1
	global_store_dwordx4 v[56:57], v[40:43], off offset:1040 sc1
	global_load_dwordx4 v[40:43], v[56:57], off offset:1552
	s_nop 0
	global_load_dwordx4 v[44:47], v[56:57], off offset:1536
	s_waitcnt vmcnt(1)
	v_pk_fma_f32 v[34:35], v[34:35], v[66:67], v[42:43]
	v_pk_fma_f32 v[32:33], v[32:33], v[64:65], v[40:41]
	global_store_dwordx4 v[56:57], v[32:35], off offset:1552 sc1
	s_waitcnt vmcnt(1)
	v_pk_fma_f32 v[38:39], v[38:39], v[70:71], v[46:47]
	v_pk_fma_f32 v[36:37], v[36:37], v[68:69], v[44:45]
	v_add_u32_e32 v32, 0x1a0, v160
	v_ashrrev_i32_e32 v33, 31, v32
	v_lshlrev_b64 v[32:33], 12, v[32:33]
	v_lshl_add_u64 v[32:33], s[6:7], 0, v[32:33]
	global_store_dwordx4 v[56:57], v[36:39], off offset:1536 sc1
	v_lshl_add_u64 v[40:41], v[32:33], 0, v[152:153]
	global_load_dwordx4 v[32:35], v[40:41], off offset:1040
	global_load_dwordx4 v[36:39], v[40:41], off offset:1024
	s_waitcnt vmcnt(1)
	v_pk_fma_f32 v[26:27], v[26:27], v[114:115], v[34:35]
	s_waitcnt vmcnt(0)
	v_pk_fma_f32 v[30:31], v[30:31], v[118:119], v[38:39]
	v_pk_fma_f32 v[28:29], v[28:29], v[116:117], v[36:37]
	v_pk_fma_f32 v[24:25], v[24:25], v[112:113], v[32:33]
	global_store_dwordx4 v[40:41], v[28:31], off offset:1024 sc1
	global_store_dwordx4 v[40:41], v[24:27], off offset:1040 sc1
	global_load_dwordx4 v[24:27], v[40:41], off offset:1552
	s_nop 0
	global_load_dwordx4 v[28:31], v[40:41], off offset:1536
	s_waitcnt vmcnt(1)
	v_pk_fma_f32 v[18:19], v[18:19], v[66:67], v[26:27]
	v_pk_fma_f32 v[16:17], v[16:17], v[64:65], v[24:25]
	global_store_dwordx4 v[40:41], v[16:19], off offset:1552 sc1
	s_waitcnt vmcnt(1)
	v_pk_fma_f32 v[22:23], v[22:23], v[70:71], v[30:31]
	v_pk_fma_f32 v[20:21], v[20:21], v[68:69], v[28:29]
	v_add_u32_e32 v16, 0x1b0, v160
	v_ashrrev_i32_e32 v17, 31, v16
	v_lshlrev_b64 v[16:17], 12, v[16:17]
	v_lshl_add_u64 v[16:17], s[6:7], 0, v[16:17]
	global_store_dwordx4 v[40:41], v[20:23], off offset:1536 sc1
	v_lshl_add_u64 v[16:17], v[16:17], 0, v[152:153]
	global_load_dwordx4 v[18:21], v[16:17], off offset:1040
	global_load_dwordx4 v[22:25], v[16:17], off offset:1024
	s_waitcnt vmcnt(1)
	v_pk_fma_f32 v[10:11], v[10:11], v[114:115], v[20:21]
	s_waitcnt vmcnt(0)
	v_pk_fma_f32 v[14:15], v[14:15], v[118:119], v[24:25]
	v_pk_fma_f32 v[12:13], v[12:13], v[116:117], v[22:23]
	v_pk_fma_f32 v[8:9], v[8:9], v[112:113], v[18:19]
	global_store_dwordx4 v[16:17], v[12:15], off offset:1024 sc1
	global_store_dwordx4 v[16:17], v[8:11], off offset:1040 sc1
	global_load_dwordx4 v[8:11], v[16:17], off offset:1552
	s_nop 0
	global_load_dwordx4 v[12:15], v[16:17], off offset:1536
	s_waitcnt vmcnt(1)
	v_pk_fma_f32 v[2:3], v[2:3], v[66:67], v[10:11]
	s_waitcnt vmcnt(0)
	v_pk_fma_f32 v[6:7], v[6:7], v[70:71], v[14:15]
	v_pk_fma_f32 v[4:5], v[4:5], v[68:69], v[12:13]
	v_pk_fma_f32 v[0:1], v[0:1], v[64:65], v[8:9]
	global_store_dwordx4 v[16:17], v[4:7], off offset:1536 sc1
	global_store_dwordx4 v[16:17], v[0:3], off offset:1552 sc1
	s_cbranch_vccz .LBB0_1588
	s_andn2_b64 vcc, exec, s[10:11]
	s_cbranch_vccnz .LBB0_1587
	s_barrier
	s_branch .LBB0_1587

.LBB0_1611:
	v_lshl_add_u32 v160, s28, 8, v154
	v_add_u32_e32 v162, 0x100, v160
	v_lshl_or_b32 v64, s29, 8, v156
	v_ashrrev_i32_e32 v163, 31, v162
	v_ashrrev_i32_e32 v65, 31, v64
	v_lshlrev_b64 v[162:163], 12, v[162:163]
	v_lshlrev_b64 v[152:153], 2, v[64:65]
	v_lshl_add_u64 v[162:163], s[6:7], 0, v[162:163]
	v_lshl_add_u64 v[68:69], s[12:13], 0, v[152:153]
	v_lshl_add_u64 v[170:171], v[162:163], 0, v[152:153]
	global_load_dwordx4 v[112:115], v[68:69], off offset:16
	global_load_dwordx4 v[116:119], v[68:69], off
	global_load_dwordx4 v[64:67], v[68:69], off offset:528
	s_nop 0
	global_load_dwordx4 v[68:71], v[68:69], off offset:512
	s_nop 0
	global_load_dwordx4 v[162:165], v[170:171], off offset:2064
	global_load_dwordx4 v[166:169], v[170:171], off offset:2048
	s_mov_b64 s[28:29], -1
	s_and_b64 vcc, s[26:27], exec
	s_waitcnt vmcnt(0)
	v_pk_fma_f32 v[138:139], v[138:139], v[114:115], v[164:165]
	v_pk_fma_f32 v[142:143], v[142:143], v[118:119], v[168:169]
	v_pk_fma_f32 v[140:141], v[140:141], v[116:117], v[166:167]
	v_pk_fma_f32 v[136:137], v[136:137], v[112:113], v[162:163]
	global_store_dwordx4 v[170:171], v[140:143], off offset:2048 sc1
	global_store_dwordx4 v[170:171], v[136:139], off offset:2064 sc1
	global_load_dwordx4 v[136:139], v[170:171], off offset:2576
	s_nop 0
	global_load_dwordx4 v[140:143], v[170:171], off offset:2560
	s_waitcnt vmcnt(1)
	v_pk_fma_f32 v[130:131], v[130:131], v[66:67], v[138:139]
	v_pk_fma_f32 v[128:129], v[128:129], v[64:65], v[136:137]
	global_store_dwordx4 v[170:171], v[128:131], off offset:2576 sc1
	s_waitcnt vmcnt(1)
	v_pk_fma_f32 v[134:135], v[134:135], v[70:71], v[142:143]
	v_pk_fma_f32 v[132:133], v[132:133], v[68:69], v[140:141]
	v_add_u32_e32 v128, 0x110, v160
	v_ashrrev_i32_e32 v129, 31, v128
	v_lshlrev_b64 v[128:129], 12, v[128:129]
	v_lshl_add_u64 v[128:129], s[6:7], 0, v[128:129]
	global_store_dwordx4 v[170:171], v[132:135], off offset:2560 sc1
	v_lshl_add_u64 v[136:137], v[128:129], 0, v[152:153]
	global_load_dwordx4 v[128:131], v[136:137], off offset:2064
	global_load_dwordx4 v[132:135], v[136:137], off offset:2048
	s_waitcnt vmcnt(1)
	v_pk_fma_f32 v[122:123], v[122:123], v[114:115], v[130:131]
	s_waitcnt vmcnt(0)
	v_pk_fma_f32 v[126:127], v[126:127], v[118:119], v[134:135]
	v_pk_fma_f32 v[124:125], v[124:125], v[116:117], v[132:133]
	v_pk_fma_f32 v[120:121], v[120:121], v[112:113], v[128:129]
	global_store_dwordx4 v[136:137], v[124:127], off offset:2048 sc1
	global_store_dwordx4 v[136:137], v[120:123], off offset:2064 sc1
	global_load_dwordx4 v[120:123], v[136:137], off offset:2576
	s_nop 0
	global_load_dwordx4 v[124:127], v[136:137], off offset:2560
	s_waitcnt vmcnt(1)
	v_pk_fma_f32 v[106:107], v[106:107], v[66:67], v[122:123]
	v_pk_fma_f32 v[104:105], v[104:105], v[64:65], v[120:121]
	global_store_dwordx4 v[136:137], v[104:107], off offset:2576 sc1
	s_waitcnt vmcnt(1)
	v_pk_fma_f32 v[110:111], v[110:111], v[70:71], v[126:127]
	v_pk_fma_f32 v[108:109], v[108:109], v[68:69], v[124:125]
	v_add_u32_e32 v104, 0x120, v160
	v_ashrrev_i32_e32 v105, 31, v104
	v_lshlrev_b64 v[104:105], 12, v[104:105]
	v_lshl_add_u64 v[104:105], s[6:7], 0, v[104:105]
	global_store_dwordx4 v[136:137], v[108:111], off offset:2560 sc1
	v_lshl_add_u64 v[120:121], v[104:105], 0, v[152:153]
	global_load_dwordx4 v[104:107], v[120:121], off offset:2064
	global_load_dwordx4 v[108:111], v[120:121], off offset:2048
	s_waitcnt vmcnt(1)
	v_pk_fma_f32 v[98:99], v[98:99], v[114:115], v[106:107]
	s_waitcnt vmcnt(0)
	v_pk_fma_f32 v[102:103], v[102:103], v[118:119], v[110:111]
	v_pk_fma_f32 v[100:101], v[100:101], v[116:117], v[108:109]
	v_pk_fma_f32 v[96:97], v[96:97], v[112:113], v[104:105]
	global_store_dwordx4 v[120:121], v[100:103], off offset:2048 sc1
	global_store_dwordx4 v[120:121], v[96:99], off offset:2064 sc1
	global_load_dwordx4 v[96:99], v[120:121], off offset:2576
	s_nop 0
	global_load_dwordx4 v[100:103], v[120:121], off offset:2560
	s_waitcnt vmcnt(1)
	v_pk_fma_f32 v[90:91], v[90:91], v[66:67], v[98:99]
	v_pk_fma_f32 v[88:89], v[88:89], v[64:65], v[96:97]
	global_store_dwordx4 v[120:121], v[88:91], off offset:2576 sc1
	s_waitcnt vmcnt(1)
	v_pk_fma_f32 v[94:95], v[94:95], v[70:71], v[102:103]
	v_pk_fma_f32 v[92:93], v[92:93], v[68:69], v[100:101]
	v_add_u32_e32 v88, 0x130, v160
	v_ashrrev_i32_e32 v89, 31, v88
	v_lshlrev_b64 v[88:89], 12, v[88:89]
	v_lshl_add_u64 v[88:89], s[6:7], 0, v[88:89]
	global_store_dwordx4 v[120:121], v[92:95], off offset:2560 sc1
	v_lshl_add_u64 v[96:97], v[88:89], 0, v[152:153]
	global_load_dwordx4 v[88:91], v[96:97], off offset:2064
	global_load_dwordx4 v[92:95], v[96:97], off offset:2048
	s_waitcnt vmcnt(1)
	v_pk_fma_f32 v[82:83], v[82:83], v[114:115], v[90:91]
	s_waitcnt vmcnt(0)
	v_pk_fma_f32 v[86:87], v[86:87], v[118:119], v[94:95]
	v_pk_fma_f32 v[84:85], v[84:85], v[116:117], v[92:93]
	v_pk_fma_f32 v[80:81], v[80:81], v[112:113], v[88:89]
	global_store_dwordx4 v[96:97], v[84:87], off offset:2048 sc1
	global_store_dwordx4 v[96:97], v[80:83], off offset:2064 sc1
	global_load_dwordx4 v[80:83], v[96:97], off offset:2576
	s_nop 0
	global_load_dwordx4 v[84:87], v[96:97], off offset:2560
	s_waitcnt vmcnt(1)
	v_pk_fma_f32 v[74:75], v[74:75], v[66:67], v[82:83]
	v_pk_fma_f32 v[72:73], v[72:73], v[64:65], v[80:81]
	global_store_dwordx4 v[96:97], v[72:75], off offset:2576 sc1
	s_waitcnt vmcnt(1)
	v_pk_fma_f32 v[78:79], v[78:79], v[70:71], v[86:87]
	v_pk_fma_f32 v[76:77], v[76:77], v[68:69], v[84:85]
	v_add_u32_e32 v72, 0x180, v160
	v_ashrrev_i32_e32 v73, 31, v72
	v_lshlrev_b64 v[72:73], 12, v[72:73]
	v_lshl_add_u64 v[72:73], s[6:7], 0, v[72:73]
	global_store_dwordx4 v[96:97], v[76:79], off offset:2560 sc1
	v_lshl_add_u64 v[80:81], v[72:73], 0, v[152:153]
	global_load_dwordx4 v[72:75], v[80:81], off offset:2064
	global_load_dwordx4 v[76:79], v[80:81], off offset:2048
	s_waitcnt vmcnt(1)
	v_pk_fma_f32 v[58:59], v[58:59], v[114:115], v[74:75]
	s_waitcnt vmcnt(0)
	v_pk_fma_f32 v[62:63], v[62:63], v[118:119], v[78:79]
	v_pk_fma_f32 v[60:61], v[60:61], v[116:117], v[76:77]
	v_pk_fma_f32 v[56:57], v[56:57], v[112:113], v[72:73]
	global_store_dwordx4 v[80:81], v[60:63], off offset:2048 sc1
	global_store_dwordx4 v[80:81], v[56:59], off offset:2064 sc1
	global_load_dwordx4 v[56:59], v[80:81], off offset:2576
	s_nop 0
	global_load_dwordx4 v[60:63], v[80:81], off offset:2560
	s_waitcnt vmcnt(1)
	v_pk_fma_f32 v[50:51], v[50:51], v[66:67], v[58:59]
	v_pk_fma_f32 v[48:49], v[48:49], v[64:65], v[56:57]
	global_store_dwordx4 v[80:81], v[48:51], off offset:2576 sc1
	s_waitcnt vmcnt(1)
	v_pk_fma_f32 v[54:55], v[54:55], v[70:71], v[62:63]
	v_pk_fma_f32 v[52:53], v[52:53], v[68:69], v[60:61]
	v_add_u32_e32 v48, 0x190, v160
	v_ashrrev_i32_e32 v49, 31, v48
	v_lshlrev_b64 v[48:49], 12, v[48:49]
	v_lshl_add_u64 v[48:49], s[6:7], 0, v[48:49]
	global_store_dwordx4 v[80:81], v[52:55], off offset:2560 sc1
	v_lshl_add_u64 v[56:57], v[48:49], 0, v[152:153]
	global_load_dwordx4 v[48:51], v[56:57], off offset:2064
	global_load_dwordx4 v[52:55], v[56:57], off offset:2048
	s_waitcnt vmcnt(1)
	v_pk_fma_f32 v[42:43], v[42:43], v[114:115], v[50:51]
	s_waitcnt vmcnt(0)
	v_pk_fma_f32 v[46:47], v[46:47], v[118:119], v[54:55]
	v_pk_fma_f32 v[44:45], v[44:45], v[116:117], v[52:53]
	v_pk_fma_f32 v[40:41], v[40:41], v[112:113], v[48:49]
	global_store_dwordx4 v[56:57], v[44:47], off offset:2048 sc1
	global_store_dwordx4 v[56:57], v[40:43], off offset:2064 sc1
	global_load_dwordx4 v[40:43], v[56:57], off offset:2576
	s_nop 0
	global_load_dwordx4 v[44:47], v[56:57], off offset:2560
	s_waitcnt vmcnt(1)
	v_pk_fma_f32 v[34:35], v[34:35], v[66:67], v[42:43]
	v_pk_fma_f32 v[32:33], v[32:33], v[64:65], v[40:41]
	global_store_dwordx4 v[56:57], v[32:35], off offset:2576 sc1
	s_waitcnt vmcnt(1)
	v_pk_fma_f32 v[38:39], v[38:39], v[70:71], v[46:47]
	v_pk_fma_f32 v[36:37], v[36:37], v[68:69], v[44:45]
	v_add_u32_e32 v32, 0x1a0, v160
	v_ashrrev_i32_e32 v33, 31, v32
	v_lshlrev_b64 v[32:33], 12, v[32:33]
	v_lshl_add_u64 v[32:33], s[6:7], 0, v[32:33]
	global_store_dwordx4 v[56:57], v[36:39], off offset:2560 sc1
	v_lshl_add_u64 v[40:41], v[32:33], 0, v[152:153]
	global_load_dwordx4 v[32:35], v[40:41], off offset:2064
	global_load_dwordx4 v[36:39], v[40:41], off offset:2048
	s_waitcnt vmcnt(1)
	v_pk_fma_f32 v[26:27], v[26:27], v[114:115], v[34:35]
	s_waitcnt vmcnt(0)
	v_pk_fma_f32 v[30:31], v[30:31], v[118:119], v[38:39]
	v_pk_fma_f32 v[28:29], v[28:29], v[116:117], v[36:37]
	v_pk_fma_f32 v[24:25], v[24:25], v[112:113], v[32:33]
	global_store_dwordx4 v[40:41], v[28:31], off offset:2048 sc1
	global_store_dwordx4 v[40:41], v[24:27], off offset:2064 sc1
	global_load_dwordx4 v[24:27], v[40:41], off offset:2576
	s_nop 0
	global_load_dwordx4 v[28:31], v[40:41], off offset:2560
	s_waitcnt vmcnt(1)
	v_pk_fma_f32 v[18:19], v[18:19], v[66:67], v[26:27]
	v_pk_fma_f32 v[16:17], v[16:17], v[64:65], v[24:25]
	global_store_dwordx4 v[40:41], v[16:19], off offset:2576 sc1
	s_waitcnt vmcnt(1)
	v_pk_fma_f32 v[22:23], v[22:23], v[70:71], v[30:31]
	v_pk_fma_f32 v[20:21], v[20:21], v[68:69], v[28:29]
	v_add_u32_e32 v16, 0x1b0, v160
	v_ashrrev_i32_e32 v17, 31, v16
	v_lshlrev_b64 v[16:17], 12, v[16:17]
	v_lshl_add_u64 v[16:17], s[6:7], 0, v[16:17]
	global_store_dwordx4 v[40:41], v[20:23], off offset:2560 sc1
	v_lshl_add_u64 v[16:17], v[16:17], 0, v[152:153]
	global_load_dwordx4 v[18:21], v[16:17], off offset:2064
	global_load_dwordx4 v[22:25], v[16:17], off offset:2048
	s_waitcnt vmcnt(1)
	v_pk_fma_f32 v[10:11], v[10:11], v[114:115], v[20:21]
	s_waitcnt vmcnt(0)
	v_pk_fma_f32 v[14:15], v[14:15], v[118:119], v[24:25]
	v_pk_fma_f32 v[12:13], v[12:13], v[116:117], v[22:23]
	v_pk_fma_f32 v[8:9], v[8:9], v[112:113], v[18:19]
	global_store_dwordx4 v[16:17], v[12:15], off offset:2048 sc1
	global_store_dwordx4 v[16:17], v[8:11], off offset:2064 sc1
	global_load_dwordx4 v[8:11], v[16:17], off offset:2576
	s_nop 0
	global_load_dwordx4 v[12:15], v[16:17], off offset:2560
	s_waitcnt vmcnt(1)
	v_pk_fma_f32 v[2:3], v[2:3], v[66:67], v[10:11]
	s_waitcnt vmcnt(0)
	v_pk_fma_f32 v[6:7], v[6:7], v[70:71], v[14:15]
	v_pk_fma_f32 v[4:5], v[4:5], v[68:69], v[12:13]
	v_pk_fma_f32 v[0:1], v[0:1], v[64:65], v[8:9]
	global_store_dwordx4 v[16:17], v[4:7], off offset:2560 sc1
	global_store_dwordx4 v[16:17], v[0:3], off offset:2576 sc1
	s_cbranch_vccz .LBB0_1604
	s_andn2_b64 vcc, exec, s[10:11]
	s_cbranch_vccnz .LBB0_1603
	s_barrier
	s_branch .LBB0_1603

.LBB0_1627:
	v_lshl_add_u32 v160, s28, 8, v154
	v_add_u32_e32 v162, 0x100, v160
	v_lshl_or_b32 v64, s29, 8, v156
	v_ashrrev_i32_e32 v163, 31, v162
	v_ashrrev_i32_e32 v65, 31, v64
	v_lshlrev_b64 v[162:163], 12, v[162:163]
	v_lshlrev_b64 v[152:153], 2, v[64:65]
	v_lshl_add_u64 v[162:163], s[6:7], 0, v[162:163]
	v_lshl_add_u64 v[68:69], s[12:13], 0, v[152:153]
	v_lshl_add_u64 v[170:171], v[162:163], 0, v[152:153]
	global_load_dwordx4 v[112:115], v[68:69], off offset:16
	global_load_dwordx4 v[116:119], v[68:69], off
	global_load_dwordx4 v[64:67], v[68:69], off offset:528
	s_nop 0
	global_load_dwordx4 v[68:71], v[68:69], off offset:512
	s_nop 0
	global_load_dwordx4 v[162:165], v[170:171], off offset:3088
	global_load_dwordx4 v[166:169], v[170:171], off offset:3072
	s_mov_b64 s[28:29], -1
	s_and_b64 vcc, s[26:27], exec
	s_waitcnt vmcnt(0)
	v_pk_fma_f32 v[138:139], v[138:139], v[114:115], v[164:165]
	v_pk_fma_f32 v[142:143], v[142:143], v[118:119], v[168:169]
	v_pk_fma_f32 v[140:141], v[140:141], v[116:117], v[166:167]
	v_pk_fma_f32 v[136:137], v[136:137], v[112:113], v[162:163]
	global_store_dwordx4 v[170:171], v[140:143], off offset:3072 sc1
	global_store_dwordx4 v[170:171], v[136:139], off offset:3088 sc1
	global_load_dwordx4 v[136:139], v[170:171], off offset:3600
	s_nop 0
	global_load_dwordx4 v[140:143], v[170:171], off offset:3584
	s_waitcnt vmcnt(1)
	v_pk_fma_f32 v[130:131], v[130:131], v[66:67], v[138:139]
	v_pk_fma_f32 v[128:129], v[128:129], v[64:65], v[136:137]
	global_store_dwordx4 v[170:171], v[128:131], off offset:3600 sc1
	s_waitcnt vmcnt(1)
	v_pk_fma_f32 v[134:135], v[134:135], v[70:71], v[142:143]
	v_pk_fma_f32 v[132:133], v[132:133], v[68:69], v[140:141]
	v_add_u32_e32 v128, 0x110, v160
	v_ashrrev_i32_e32 v129, 31, v128
	v_lshlrev_b64 v[128:129], 12, v[128:129]
	v_lshl_add_u64 v[128:129], s[6:7], 0, v[128:129]
	global_store_dwordx4 v[170:171], v[132:135], off offset:3584 sc1
	v_lshl_add_u64 v[136:137], v[128:129], 0, v[152:153]
	global_load_dwordx4 v[128:131], v[136:137], off offset:3088
	global_load_dwordx4 v[132:135], v[136:137], off offset:3072
	s_waitcnt vmcnt(1)
	v_pk_fma_f32 v[122:123], v[122:123], v[114:115], v[130:131]
	s_waitcnt vmcnt(0)
	v_pk_fma_f32 v[126:127], v[126:127], v[118:119], v[134:135]
	v_pk_fma_f32 v[124:125], v[124:125], v[116:117], v[132:133]
	v_pk_fma_f32 v[120:121], v[120:121], v[112:113], v[128:129]
	global_store_dwordx4 v[136:137], v[124:127], off offset:3072 sc1
	global_store_dwordx4 v[136:137], v[120:123], off offset:3088 sc1
	global_load_dwordx4 v[120:123], v[136:137], off offset:3600
	s_nop 0
	global_load_dwordx4 v[124:127], v[136:137], off offset:3584
	s_waitcnt vmcnt(1)
	v_pk_fma_f32 v[106:107], v[106:107], v[66:67], v[122:123]
	v_pk_fma_f32 v[104:105], v[104:105], v[64:65], v[120:121]
	global_store_dwordx4 v[136:137], v[104:107], off offset:3600 sc1
	s_waitcnt vmcnt(1)
	v_pk_fma_f32 v[110:111], v[110:111], v[70:71], v[126:127]
	v_pk_fma_f32 v[108:109], v[108:109], v[68:69], v[124:125]
	v_add_u32_e32 v104, 0x120, v160
	v_ashrrev_i32_e32 v105, 31, v104
	v_lshlrev_b64 v[104:105], 12, v[104:105]
	v_lshl_add_u64 v[104:105], s[6:7], 0, v[104:105]
	global_store_dwordx4 v[136:137], v[108:111], off offset:3584 sc1
	v_lshl_add_u64 v[120:121], v[104:105], 0, v[152:153]
	global_load_dwordx4 v[104:107], v[120:121], off offset:3088
	global_load_dwordx4 v[108:111], v[120:121], off offset:3072
	s_waitcnt vmcnt(1)
	v_pk_fma_f32 v[98:99], v[98:99], v[114:115], v[106:107]
	s_waitcnt vmcnt(0)
	v_pk_fma_f32 v[102:103], v[102:103], v[118:119], v[110:111]
	v_pk_fma_f32 v[100:101], v[100:101], v[116:117], v[108:109]
	v_pk_fma_f32 v[96:97], v[96:97], v[112:113], v[104:105]
	global_store_dwordx4 v[120:121], v[100:103], off offset:3072 sc1
	global_store_dwordx4 v[120:121], v[96:99], off offset:3088 sc1
	global_load_dwordx4 v[96:99], v[120:121], off offset:3600
	s_nop 0
	global_load_dwordx4 v[100:103], v[120:121], off offset:3584
	s_waitcnt vmcnt(1)
	v_pk_fma_f32 v[90:91], v[90:91], v[66:67], v[98:99]
	v_pk_fma_f32 v[88:89], v[88:89], v[64:65], v[96:97]
	global_store_dwordx4 v[120:121], v[88:91], off offset:3600 sc1
	s_waitcnt vmcnt(1)
	v_pk_fma_f32 v[94:95], v[94:95], v[70:71], v[102:103]
	v_pk_fma_f32 v[92:93], v[92:93], v[68:69], v[100:101]
	v_add_u32_e32 v88, 0x130, v160
	v_ashrrev_i32_e32 v89, 31, v88
	v_lshlrev_b64 v[88:89], 12, v[88:89]
	v_lshl_add_u64 v[88:89], s[6:7], 0, v[88:89]
	global_store_dwordx4 v[120:121], v[92:95], off offset:3584 sc1
	v_lshl_add_u64 v[96:97], v[88:89], 0, v[152:153]
	global_load_dwordx4 v[88:91], v[96:97], off offset:3088
	global_load_dwordx4 v[92:95], v[96:97], off offset:3072
	s_waitcnt vmcnt(1)
	v_pk_fma_f32 v[82:83], v[82:83], v[114:115], v[90:91]
	s_waitcnt vmcnt(0)
	v_pk_fma_f32 v[86:87], v[86:87], v[118:119], v[94:95]
	v_pk_fma_f32 v[84:85], v[84:85], v[116:117], v[92:93]
	v_pk_fma_f32 v[80:81], v[80:81], v[112:113], v[88:89]
	global_store_dwordx4 v[96:97], v[84:87], off offset:3072 sc1
	global_store_dwordx4 v[96:97], v[80:83], off offset:3088 sc1
	global_load_dwordx4 v[80:83], v[96:97], off offset:3600
	s_nop 0
	global_load_dwordx4 v[84:87], v[96:97], off offset:3584
	s_waitcnt vmcnt(1)
	v_pk_fma_f32 v[74:75], v[74:75], v[66:67], v[82:83]
	v_pk_fma_f32 v[72:73], v[72:73], v[64:65], v[80:81]
	global_store_dwordx4 v[96:97], v[72:75], off offset:3600 sc1
	s_waitcnt vmcnt(1)
	v_pk_fma_f32 v[78:79], v[78:79], v[70:71], v[86:87]
	v_pk_fma_f32 v[76:77], v[76:77], v[68:69], v[84:85]
	v_add_u32_e32 v72, 0x180, v160
	v_ashrrev_i32_e32 v73, 31, v72
	v_lshlrev_b64 v[72:73], 12, v[72:73]
	v_lshl_add_u64 v[72:73], s[6:7], 0, v[72:73]
	global_store_dwordx4 v[96:97], v[76:79], off offset:3584 sc1
	v_lshl_add_u64 v[80:81], v[72:73], 0, v[152:153]
	global_load_dwordx4 v[72:75], v[80:81], off offset:3088
	global_load_dwordx4 v[76:79], v[80:81], off offset:3072
	s_waitcnt vmcnt(1)
	v_pk_fma_f32 v[58:59], v[58:59], v[114:115], v[74:75]
	s_waitcnt vmcnt(0)
	v_pk_fma_f32 v[62:63], v[62:63], v[118:119], v[78:79]
	v_pk_fma_f32 v[60:61], v[60:61], v[116:117], v[76:77]
	v_pk_fma_f32 v[56:57], v[56:57], v[112:113], v[72:73]
	global_store_dwordx4 v[80:81], v[60:63], off offset:3072 sc1
	global_store_dwordx4 v[80:81], v[56:59], off offset:3088 sc1
	global_load_dwordx4 v[56:59], v[80:81], off offset:3600
	s_nop 0
	global_load_dwordx4 v[60:63], v[80:81], off offset:3584
	s_waitcnt vmcnt(1)
	v_pk_fma_f32 v[50:51], v[50:51], v[66:67], v[58:59]
	v_pk_fma_f32 v[48:49], v[48:49], v[64:65], v[56:57]
	global_store_dwordx4 v[80:81], v[48:51], off offset:3600 sc1
	s_waitcnt vmcnt(1)
	v_pk_fma_f32 v[54:55], v[54:55], v[70:71], v[62:63]
	v_pk_fma_f32 v[52:53], v[52:53], v[68:69], v[60:61]
	v_add_u32_e32 v48, 0x190, v160
	v_ashrrev_i32_e32 v49, 31, v48
	v_lshlrev_b64 v[48:49], 12, v[48:49]
	v_lshl_add_u64 v[48:49], s[6:7], 0, v[48:49]
	global_store_dwordx4 v[80:81], v[52:55], off offset:3584 sc1
	v_lshl_add_u64 v[56:57], v[48:49], 0, v[152:153]
	global_load_dwordx4 v[48:51], v[56:57], off offset:3088
	global_load_dwordx4 v[52:55], v[56:57], off offset:3072
	s_waitcnt vmcnt(1)
	v_pk_fma_f32 v[42:43], v[42:43], v[114:115], v[50:51]
	s_waitcnt vmcnt(0)
	v_pk_fma_f32 v[46:47], v[46:47], v[118:119], v[54:55]
	v_pk_fma_f32 v[44:45], v[44:45], v[116:117], v[52:53]
	v_pk_fma_f32 v[40:41], v[40:41], v[112:113], v[48:49]
	global_store_dwordx4 v[56:57], v[44:47], off offset:3072 sc1
	global_store_dwordx4 v[56:57], v[40:43], off offset:3088 sc1
	global_load_dwordx4 v[40:43], v[56:57], off offset:3600
	s_nop 0
	global_load_dwordx4 v[44:47], v[56:57], off offset:3584
	s_waitcnt vmcnt(1)
	v_pk_fma_f32 v[34:35], v[34:35], v[66:67], v[42:43]
	v_pk_fma_f32 v[32:33], v[32:33], v[64:65], v[40:41]
	global_store_dwordx4 v[56:57], v[32:35], off offset:3600 sc1
	s_waitcnt vmcnt(1)
	v_pk_fma_f32 v[38:39], v[38:39], v[70:71], v[46:47]
	v_pk_fma_f32 v[36:37], v[36:37], v[68:69], v[44:45]
	v_add_u32_e32 v32, 0x1a0, v160
	v_ashrrev_i32_e32 v33, 31, v32
	v_lshlrev_b64 v[32:33], 12, v[32:33]
	v_lshl_add_u64 v[32:33], s[6:7], 0, v[32:33]
	global_store_dwordx4 v[56:57], v[36:39], off offset:3584 sc1
	v_lshl_add_u64 v[40:41], v[32:33], 0, v[152:153]
	global_load_dwordx4 v[32:35], v[40:41], off offset:3088
	global_load_dwordx4 v[36:39], v[40:41], off offset:3072
	s_waitcnt vmcnt(1)
	v_pk_fma_f32 v[26:27], v[26:27], v[114:115], v[34:35]
	s_waitcnt vmcnt(0)
	v_pk_fma_f32 v[30:31], v[30:31], v[118:119], v[38:39]
	v_pk_fma_f32 v[28:29], v[28:29], v[116:117], v[36:37]
	v_pk_fma_f32 v[24:25], v[24:25], v[112:113], v[32:33]
	global_store_dwordx4 v[40:41], v[28:31], off offset:3072 sc1
	global_store_dwordx4 v[40:41], v[24:27], off offset:3088 sc1
	global_load_dwordx4 v[24:27], v[40:41], off offset:3600
	s_nop 0
	global_load_dwordx4 v[28:31], v[40:41], off offset:3584
	s_waitcnt vmcnt(1)
	v_pk_fma_f32 v[18:19], v[18:19], v[66:67], v[26:27]
	v_pk_fma_f32 v[16:17], v[16:17], v[64:65], v[24:25]
	global_store_dwordx4 v[40:41], v[16:19], off offset:3600 sc1
	s_waitcnt vmcnt(1)
	v_pk_fma_f32 v[22:23], v[22:23], v[70:71], v[30:31]
	v_pk_fma_f32 v[20:21], v[20:21], v[68:69], v[28:29]
	v_add_u32_e32 v16, 0x1b0, v160
	v_ashrrev_i32_e32 v17, 31, v16
	v_lshlrev_b64 v[16:17], 12, v[16:17]
	v_lshl_add_u64 v[16:17], s[6:7], 0, v[16:17]
	global_store_dwordx4 v[40:41], v[20:23], off offset:3584 sc1
	v_lshl_add_u64 v[16:17], v[16:17], 0, v[152:153]
	global_load_dwordx4 v[18:21], v[16:17], off offset:3088
	global_load_dwordx4 v[22:25], v[16:17], off offset:3072
	s_waitcnt vmcnt(1)
	v_pk_fma_f32 v[10:11], v[10:11], v[114:115], v[20:21]
	s_waitcnt vmcnt(0)
	v_pk_fma_f32 v[14:15], v[14:15], v[118:119], v[24:25]
	v_pk_fma_f32 v[12:13], v[12:13], v[116:117], v[22:23]
	v_pk_fma_f32 v[8:9], v[8:9], v[112:113], v[18:19]
	global_store_dwordx4 v[16:17], v[12:15], off offset:3072 sc1
	global_store_dwordx4 v[16:17], v[8:11], off offset:3088 sc1
	global_load_dwordx4 v[8:11], v[16:17], off offset:3600
	s_nop 0
	global_load_dwordx4 v[12:15], v[16:17], off offset:3584
	s_waitcnt vmcnt(1)
	v_pk_fma_f32 v[2:3], v[2:3], v[66:67], v[10:11]
	s_waitcnt vmcnt(0)
	v_pk_fma_f32 v[6:7], v[6:7], v[70:71], v[14:15]
	v_pk_fma_f32 v[4:5], v[4:5], v[68:69], v[12:13]
	v_pk_fma_f32 v[0:1], v[0:1], v[64:65], v[8:9]
	global_store_dwordx4 v[16:17], v[4:7], off offset:3584 sc1
	global_store_dwordx4 v[16:17], v[0:3], off offset:3600 sc1
	s_cbranch_vccz .LBB0_1620
	s_andn2_b64 vcc, exec, s[10:11]
	s_cbranch_vccnz .LBB0_1619
	s_barrier
	s_branch .LBB0_1619

.LBB0_2405:
	v_lshl_add_u32 v168, s26, 8, v162
	v_add_u32_e32 v170, 0x100, v168
	v_lshl_or_b32 v64, s27, 8, v164
	v_ashrrev_i32_e32 v171, 31, v170
	v_ashrrev_i32_e32 v65, 31, v64
	v_lshlrev_b64 v[170:171], 12, v[170:171]
	v_lshlrev_b64 v[160:161], 2, v[64:65]
	v_lshl_add_u64 v[170:171], s[8:9], 0, v[170:171]
	v_lshl_add_u64 v[68:69], s[12:13], 0, v[160:161]
	v_lshl_add_u64 v[178:179], v[170:171], 0, v[160:161]
	global_load_dwordx4 v[112:115], v[68:69], off offset:16
	global_load_dwordx4 v[116:119], v[68:69], off
	global_load_dwordx4 v[64:67], v[68:69], off offset:528
	s_nop 0
	global_load_dwordx4 v[68:71], v[68:69], off offset:512
	s_nop 0
	global_load_dwordx4 v[170:173], v[178:179], off offset:16
	global_load_dwordx4 v[174:177], v[178:179], off
	s_mov_b64 s[26:27], -1
	s_andn2_b64 vcc, exec, s[6:7]
	s_waitcnt vmcnt(0)
	v_pk_fma_f32 v[138:139], v[138:139], v[114:115], v[172:173]
	v_pk_fma_f32 v[142:143], v[142:143], v[118:119], v[176:177]
	v_pk_fma_f32 v[140:141], v[140:141], v[116:117], v[174:175]
	v_pk_fma_f32 v[136:137], v[136:137], v[112:113], v[170:171]
	global_store_dwordx4 v[178:179], v[140:143], off sc1
	global_store_dwordx4 v[178:179], v[136:139], off offset:16 sc1
	global_load_dwordx4 v[136:139], v[178:179], off offset:528
	s_nop 0
	global_load_dwordx4 v[140:143], v[178:179], off offset:512
	s_waitcnt vmcnt(1)
	v_pk_fma_f32 v[130:131], v[130:131], v[66:67], v[138:139]
	v_pk_fma_f32 v[128:129], v[128:129], v[64:65], v[136:137]
	global_store_dwordx4 v[178:179], v[128:131], off offset:528 sc1
	s_waitcnt vmcnt(1)
	v_pk_fma_f32 v[134:135], v[134:135], v[70:71], v[142:143]
	v_pk_fma_f32 v[132:133], v[132:133], v[68:69], v[140:141]
	v_add_u32_e32 v128, 0x110, v168
	v_ashrrev_i32_e32 v129, 31, v128
	v_lshlrev_b64 v[128:129], 12, v[128:129]
	v_lshl_add_u64 v[128:129], s[8:9], 0, v[128:129]
	global_store_dwordx4 v[178:179], v[132:135], off offset:512 sc1
	v_lshl_add_u64 v[136:137], v[128:129], 0, v[160:161]
	global_load_dwordx4 v[128:131], v[136:137], off offset:16
	global_load_dwordx4 v[132:135], v[136:137], off
	s_waitcnt vmcnt(1)
	v_pk_fma_f32 v[122:123], v[122:123], v[114:115], v[130:131]
	s_waitcnt vmcnt(0)
	v_pk_fma_f32 v[126:127], v[126:127], v[118:119], v[134:135]
	v_pk_fma_f32 v[124:125], v[124:125], v[116:117], v[132:133]
	v_pk_fma_f32 v[120:121], v[120:121], v[112:113], v[128:129]
	global_store_dwordx4 v[136:137], v[124:127], off sc1
	global_store_dwordx4 v[136:137], v[120:123], off offset:16 sc1
	global_load_dwordx4 v[120:123], v[136:137], off offset:528
	s_nop 0
	global_load_dwordx4 v[124:127], v[136:137], off offset:512
	s_waitcnt vmcnt(1)
	v_pk_fma_f32 v[106:107], v[106:107], v[66:67], v[122:123]
	v_pk_fma_f32 v[104:105], v[104:105], v[64:65], v[120:121]
	global_store_dwordx4 v[136:137], v[104:107], off offset:528 sc1
	s_waitcnt vmcnt(1)
	v_pk_fma_f32 v[110:111], v[110:111], v[70:71], v[126:127]
	v_pk_fma_f32 v[108:109], v[108:109], v[68:69], v[124:125]
	v_add_u32_e32 v104, 0x120, v168
	v_ashrrev_i32_e32 v105, 31, v104
	v_lshlrev_b64 v[104:105], 12, v[104:105]
	v_lshl_add_u64 v[104:105], s[8:9], 0, v[104:105]
	global_store_dwordx4 v[136:137], v[108:111], off offset:512 sc1
	v_lshl_add_u64 v[120:121], v[104:105], 0, v[160:161]
	global_load_dwordx4 v[104:107], v[120:121], off offset:16
	global_load_dwordx4 v[108:111], v[120:121], off
	s_waitcnt vmcnt(1)
	v_pk_fma_f32 v[98:99], v[98:99], v[114:115], v[106:107]
	s_waitcnt vmcnt(0)
	v_pk_fma_f32 v[102:103], v[102:103], v[118:119], v[110:111]
	v_pk_fma_f32 v[100:101], v[100:101], v[116:117], v[108:109]
	v_pk_fma_f32 v[96:97], v[96:97], v[112:113], v[104:105]
	global_store_dwordx4 v[120:121], v[100:103], off sc1
	global_store_dwordx4 v[120:121], v[96:99], off offset:16 sc1
	global_load_dwordx4 v[96:99], v[120:121], off offset:528
	s_nop 0
	global_load_dwordx4 v[100:103], v[120:121], off offset:512
	s_waitcnt vmcnt(1)
	v_pk_fma_f32 v[90:91], v[90:91], v[66:67], v[98:99]
	v_pk_fma_f32 v[88:89], v[88:89], v[64:65], v[96:97]
	global_store_dwordx4 v[120:121], v[88:91], off offset:528 sc1
	s_waitcnt vmcnt(1)
	v_pk_fma_f32 v[94:95], v[94:95], v[70:71], v[102:103]
	v_pk_fma_f32 v[92:93], v[92:93], v[68:69], v[100:101]
	v_add_u32_e32 v88, 0x130, v168
	v_ashrrev_i32_e32 v89, 31, v88
	v_lshlrev_b64 v[88:89], 12, v[88:89]
	v_lshl_add_u64 v[88:89], s[8:9], 0, v[88:89]
	global_store_dwordx4 v[120:121], v[92:95], off offset:512 sc1
	v_lshl_add_u64 v[96:97], v[88:89], 0, v[160:161]
	global_load_dwordx4 v[88:91], v[96:97], off offset:16
	global_load_dwordx4 v[92:95], v[96:97], off
	s_waitcnt vmcnt(1)
	v_pk_fma_f32 v[82:83], v[82:83], v[114:115], v[90:91]
	s_waitcnt vmcnt(0)
	v_pk_fma_f32 v[86:87], v[86:87], v[118:119], v[94:95]
	v_pk_fma_f32 v[84:85], v[84:85], v[116:117], v[92:93]
	v_pk_fma_f32 v[80:81], v[80:81], v[112:113], v[88:89]
	global_store_dwordx4 v[96:97], v[84:87], off sc1
	global_store_dwordx4 v[96:97], v[80:83], off offset:16 sc1
	global_load_dwordx4 v[80:83], v[96:97], off offset:528
	s_nop 0
	global_load_dwordx4 v[84:87], v[96:97], off offset:512
	s_waitcnt vmcnt(1)
	v_pk_fma_f32 v[74:75], v[74:75], v[66:67], v[82:83]
	v_pk_fma_f32 v[72:73], v[72:73], v[64:65], v[80:81]
	global_store_dwordx4 v[96:97], v[72:75], off offset:528 sc1
	s_waitcnt vmcnt(1)
	v_pk_fma_f32 v[78:79], v[78:79], v[70:71], v[86:87]
	v_pk_fma_f32 v[76:77], v[76:77], v[68:69], v[84:85]
	v_add_u32_e32 v72, 0x180, v168
	v_ashrrev_i32_e32 v73, 31, v72
	v_lshlrev_b64 v[72:73], 12, v[72:73]
	v_lshl_add_u64 v[72:73], s[8:9], 0, v[72:73]
	global_store_dwordx4 v[96:97], v[76:79], off offset:512 sc1
	v_lshl_add_u64 v[80:81], v[72:73], 0, v[160:161]
	global_load_dwordx4 v[72:75], v[80:81], off offset:16
	global_load_dwordx4 v[76:79], v[80:81], off
	s_waitcnt vmcnt(1)
	v_pk_fma_f32 v[58:59], v[58:59], v[114:115], v[74:75]
	s_waitcnt vmcnt(0)
	v_pk_fma_f32 v[62:63], v[62:63], v[118:119], v[78:79]
	v_pk_fma_f32 v[60:61], v[60:61], v[116:117], v[76:77]
	v_pk_fma_f32 v[56:57], v[56:57], v[112:113], v[72:73]
	global_store_dwordx4 v[80:81], v[60:63], off sc1
	global_store_dwordx4 v[80:81], v[56:59], off offset:16 sc1
	global_load_dwordx4 v[56:59], v[80:81], off offset:528
	s_nop 0
	global_load_dwordx4 v[60:63], v[80:81], off offset:512
	s_waitcnt vmcnt(1)
	v_pk_fma_f32 v[50:51], v[50:51], v[66:67], v[58:59]
	v_pk_fma_f32 v[48:49], v[48:49], v[64:65], v[56:57]
	global_store_dwordx4 v[80:81], v[48:51], off offset:528 sc1
	s_waitcnt vmcnt(1)
	v_pk_fma_f32 v[54:55], v[54:55], v[70:71], v[62:63]
	v_pk_fma_f32 v[52:53], v[52:53], v[68:69], v[60:61]
	v_add_u32_e32 v48, 0x190, v168
	v_ashrrev_i32_e32 v49, 31, v48
	v_lshlrev_b64 v[48:49], 12, v[48:49]
	v_lshl_add_u64 v[48:49], s[8:9], 0, v[48:49]
	global_store_dwordx4 v[80:81], v[52:55], off offset:512 sc1
	v_lshl_add_u64 v[56:57], v[48:49], 0, v[160:161]
	global_load_dwordx4 v[48:51], v[56:57], off offset:16
	global_load_dwordx4 v[52:55], v[56:57], off
	s_waitcnt vmcnt(1)
	v_pk_fma_f32 v[42:43], v[42:43], v[114:115], v[50:51]
	s_waitcnt vmcnt(0)
	v_pk_fma_f32 v[46:47], v[46:47], v[118:119], v[54:55]
	v_pk_fma_f32 v[44:45], v[44:45], v[116:117], v[52:53]
	v_pk_fma_f32 v[40:41], v[40:41], v[112:113], v[48:49]
	global_store_dwordx4 v[56:57], v[44:47], off sc1
	global_store_dwordx4 v[56:57], v[40:43], off offset:16 sc1
	global_load_dwordx4 v[40:43], v[56:57], off offset:528
	s_nop 0
	global_load_dwordx4 v[44:47], v[56:57], off offset:512
	s_waitcnt vmcnt(1)
	v_pk_fma_f32 v[34:35], v[34:35], v[66:67], v[42:43]
	v_pk_fma_f32 v[32:33], v[32:33], v[64:65], v[40:41]
	global_store_dwordx4 v[56:57], v[32:35], off offset:528 sc1
	s_waitcnt vmcnt(1)
	v_pk_fma_f32 v[38:39], v[38:39], v[70:71], v[46:47]
	v_pk_fma_f32 v[36:37], v[36:37], v[68:69], v[44:45]
	v_add_u32_e32 v32, 0x1a0, v168
	v_ashrrev_i32_e32 v33, 31, v32
	v_lshlrev_b64 v[32:33], 12, v[32:33]
	v_lshl_add_u64 v[32:33], s[8:9], 0, v[32:33]
	global_store_dwordx4 v[56:57], v[36:39], off offset:512 sc1
	v_lshl_add_u64 v[40:41], v[32:33], 0, v[160:161]
	global_load_dwordx4 v[32:35], v[40:41], off offset:16
	global_load_dwordx4 v[36:39], v[40:41], off
	s_waitcnt vmcnt(1)
	v_pk_fma_f32 v[26:27], v[26:27], v[114:115], v[34:35]
	s_waitcnt vmcnt(0)
	v_pk_fma_f32 v[30:31], v[30:31], v[118:119], v[38:39]
	v_pk_fma_f32 v[28:29], v[28:29], v[116:117], v[36:37]
	v_pk_fma_f32 v[24:25], v[24:25], v[112:113], v[32:33]
	global_store_dwordx4 v[40:41], v[28:31], off sc1
	global_store_dwordx4 v[40:41], v[24:27], off offset:16 sc1
	global_load_dwordx4 v[24:27], v[40:41], off offset:528
	s_nop 0
	global_load_dwordx4 v[28:31], v[40:41], off offset:512
	s_waitcnt vmcnt(1)
	v_pk_fma_f32 v[18:19], v[18:19], v[66:67], v[26:27]
	v_pk_fma_f32 v[16:17], v[16:17], v[64:65], v[24:25]
	global_store_dwordx4 v[40:41], v[16:19], off offset:528 sc1
	s_waitcnt vmcnt(1)
	v_pk_fma_f32 v[22:23], v[22:23], v[70:71], v[30:31]
	v_pk_fma_f32 v[20:21], v[20:21], v[68:69], v[28:29]
	v_add_u32_e32 v16, 0x1b0, v168
	v_ashrrev_i32_e32 v17, 31, v16
	v_lshlrev_b64 v[16:17], 12, v[16:17]
	v_lshl_add_u64 v[16:17], s[8:9], 0, v[16:17]
	global_store_dwordx4 v[40:41], v[20:23], off offset:512 sc1
	v_lshl_add_u64 v[16:17], v[16:17], 0, v[160:161]
	global_load_dwordx4 v[18:21], v[16:17], off offset:16
	global_load_dwordx4 v[22:25], v[16:17], off
	s_waitcnt vmcnt(1)
	v_pk_fma_f32 v[10:11], v[10:11], v[114:115], v[20:21]
	s_waitcnt vmcnt(0)
	v_pk_fma_f32 v[14:15], v[14:15], v[118:119], v[24:25]
	v_pk_fma_f32 v[12:13], v[12:13], v[116:117], v[22:23]
	v_pk_fma_f32 v[8:9], v[8:9], v[112:113], v[18:19]
	global_store_dwordx4 v[16:17], v[12:15], off sc1
	global_store_dwordx4 v[16:17], v[8:11], off offset:16 sc1
	global_load_dwordx4 v[8:11], v[16:17], off offset:528
	s_nop 0
	global_load_dwordx4 v[12:15], v[16:17], off offset:512
	s_waitcnt vmcnt(1)
	v_pk_fma_f32 v[2:3], v[2:3], v[66:67], v[10:11]
	s_waitcnt vmcnt(0)
	v_pk_fma_f32 v[6:7], v[6:7], v[70:71], v[14:15]
	v_pk_fma_f32 v[4:5], v[4:5], v[68:69], v[12:13]
	v_pk_fma_f32 v[0:1], v[0:1], v[64:65], v[8:9]
	global_store_dwordx4 v[16:17], v[4:7], off offset:512 sc1
	global_store_dwordx4 v[16:17], v[0:3], off offset:528 sc1
	s_cbranch_vccnz .LBB0_2398
	s_andn2_b64 vcc, exec, s[10:11]
	s_cbranch_vccnz .LBB0_2397
	s_barrier
	s_branch .LBB0_2397

.LBB0_2611:
	v_lshl_or_b32 v144, s52, 8, v164
	v_ashrrev_i32_e32 v145, 31, v144
	v_lshlrev_b64 v[152:153], 2, v[144:145]
	v_lshl_add_u64 v[172:173], s[14:15], 0, v[152:153]
	global_load_dwordx4 v[144:147], v[172:173], off offset:16
	global_load_dwordx4 v[148:151], v[172:173], off
	s_mov_b64 s[22:23], -1
	s_and_b64 vcc, exec, s[6:7]
	s_waitcnt vmcnt(0)
	v_pk_mul_f32 v[154:155], v[146:147], 0.5 op_sel_hi:[1,0]
	v_pk_mul_f32 v[156:157], v[144:145], 0.5 op_sel_hi:[1,0]
	global_load_dwordx4 v[168:171], v[172:173], off offset:528
	global_load_dwordx4 v[144:147], v[172:173], off offset:512
	v_pk_mul_f32 v[160:161], v[148:149], 0.5 op_sel_hi:[1,0]
	v_pk_mul_f32 v[158:159], v[150:151], 0.5 op_sel_hi:[1,0]
	s_waitcnt vmcnt(0)
	v_pk_mul_f32 v[148:149], v[146:147], 0.5 op_sel_hi:[1,0]
	v_pk_mul_f32 v[146:147], v[168:169], 0.5 op_sel_hi:[1,0]
	v_lshl_add_u32 v168, s51, 8, v162
	v_pk_mul_f32 v[150:151], v[144:145], 0.5 op_sel_hi:[1,0]
	v_pk_mul_f32 v[144:145], v[170:171], 0.5 op_sel_hi:[1,0]
	v_add_u32_e32 v170, 0x100, v168
	v_ashrrev_i32_e32 v171, 31, v170
	v_lshlrev_b64 v[170:171], 12, v[170:171]
	v_lshl_add_u64 v[170:171], s[10:11], 0, v[170:171]
	v_lshl_add_u64 v[178:179], v[170:171], 0, v[152:153]
	global_load_dwordx4 v[170:173], v[178:179], off offset:16
	global_load_dwordx4 v[174:177], v[178:179], off
	s_waitcnt vmcnt(1)
	v_pk_fma_f32 v[122:123], v[122:123], v[154:155], v[172:173]
	s_waitcnt vmcnt(0)
	v_pk_fma_f32 v[126:127], v[126:127], v[158:159], v[176:177]
	v_pk_fma_f32 v[124:125], v[124:125], v[160:161], v[174:175]
	v_pk_fma_f32 v[120:121], v[120:121], v[156:157], v[170:171]
	global_store_dwordx4 v[178:179], v[124:127], off sc1
	global_store_dwordx4 v[178:179], v[120:123], off offset:16 sc1
	global_load_dwordx4 v[120:123], v[178:179], off offset:528
	s_nop 0
	global_load_dwordx4 v[124:127], v[178:179], off offset:512
	s_waitcnt vmcnt(1)
	v_pk_fma_f32 v[114:115], v[114:115], v[144:145], v[122:123]
	v_pk_fma_f32 v[112:113], v[112:113], v[146:147], v[120:121]
	global_store_dwordx4 v[178:179], v[112:115], off offset:528 sc1
	s_waitcnt vmcnt(1)
	v_pk_fma_f32 v[118:119], v[118:119], v[148:149], v[126:127]
	v_pk_fma_f32 v[116:117], v[116:117], v[150:151], v[124:125]
	v_add_u32_e32 v112, 0x110, v168
	v_ashrrev_i32_e32 v113, 31, v112
	v_lshlrev_b64 v[112:113], 12, v[112:113]
	v_lshl_add_u64 v[112:113], s[10:11], 0, v[112:113]
	global_store_dwordx4 v[178:179], v[116:119], off offset:512 sc1
	v_lshl_add_u64 v[120:121], v[112:113], 0, v[152:153]
	global_load_dwordx4 v[112:115], v[120:121], off offset:16
	global_load_dwordx4 v[116:119], v[120:121], off
	s_waitcnt vmcnt(1)
	v_pk_fma_f32 v[106:107], v[106:107], v[154:155], v[114:115]
	s_waitcnt vmcnt(0)
	v_pk_fma_f32 v[110:111], v[110:111], v[158:159], v[118:119]
	v_pk_fma_f32 v[108:109], v[108:109], v[160:161], v[116:117]
	v_pk_fma_f32 v[104:105], v[104:105], v[156:157], v[112:113]
	global_store_dwordx4 v[120:121], v[108:111], off sc1
	global_store_dwordx4 v[120:121], v[104:107], off offset:16 sc1
	global_load_dwordx4 v[104:107], v[120:121], off offset:528
	s_nop 0
	global_load_dwordx4 v[108:111], v[120:121], off offset:512
	s_waitcnt vmcnt(1)
	v_pk_fma_f32 v[98:99], v[98:99], v[144:145], v[106:107]
	v_pk_fma_f32 v[96:97], v[96:97], v[146:147], v[104:105]
	global_store_dwordx4 v[120:121], v[96:99], off offset:528 sc1
	s_waitcnt vmcnt(1)
	v_pk_fma_f32 v[102:103], v[102:103], v[148:149], v[110:111]
	v_pk_fma_f32 v[100:101], v[100:101], v[150:151], v[108:109]
	v_add_u32_e32 v96, 0x120, v168
	v_ashrrev_i32_e32 v97, 31, v96
	v_lshlrev_b64 v[96:97], 12, v[96:97]
	v_lshl_add_u64 v[96:97], s[10:11], 0, v[96:97]
	global_store_dwordx4 v[120:121], v[100:103], off offset:512 sc1
	v_lshl_add_u64 v[104:105], v[96:97], 0, v[152:153]
	global_load_dwordx4 v[96:99], v[104:105], off offset:16
	global_load_dwordx4 v[100:103], v[104:105], off
	s_waitcnt vmcnt(1)
	v_pk_fma_f32 v[90:91], v[90:91], v[154:155], v[98:99]
	s_waitcnt vmcnt(0)
	v_pk_fma_f32 v[94:95], v[94:95], v[158:159], v[102:103]
	v_pk_fma_f32 v[92:93], v[92:93], v[160:161], v[100:101]
	v_pk_fma_f32 v[88:89], v[88:89], v[156:157], v[96:97]
	global_store_dwordx4 v[104:105], v[92:95], off sc1
	global_store_dwordx4 v[104:105], v[88:91], off offset:16 sc1
	global_load_dwordx4 v[88:91], v[104:105], off offset:528
	s_nop 0
	global_load_dwordx4 v[92:95], v[104:105], off offset:512
	s_waitcnt vmcnt(1)
	v_pk_fma_f32 v[82:83], v[82:83], v[144:145], v[90:91]
	v_pk_fma_f32 v[80:81], v[80:81], v[146:147], v[88:89]
	global_store_dwordx4 v[104:105], v[80:83], off offset:528 sc1
	s_waitcnt vmcnt(1)
	v_pk_fma_f32 v[86:87], v[86:87], v[148:149], v[94:95]
	v_pk_fma_f32 v[84:85], v[84:85], v[150:151], v[92:93]
	v_add_u32_e32 v80, 0x130, v168
	v_ashrrev_i32_e32 v81, 31, v80
	v_lshlrev_b64 v[80:81], 12, v[80:81]
	v_lshl_add_u64 v[80:81], s[10:11], 0, v[80:81]
	global_store_dwordx4 v[104:105], v[84:87], off offset:512 sc1
	v_lshl_add_u64 v[88:89], v[80:81], 0, v[152:153]
	global_load_dwordx4 v[80:83], v[88:89], off offset:16
	global_load_dwordx4 v[84:87], v[88:89], off
	s_waitcnt vmcnt(1)
	v_pk_fma_f32 v[74:75], v[74:75], v[154:155], v[82:83]
	s_waitcnt vmcnt(0)
	v_pk_fma_f32 v[78:79], v[78:79], v[158:159], v[86:87]
	v_pk_fma_f32 v[76:77], v[76:77], v[160:161], v[84:85]
	v_pk_fma_f32 v[72:73], v[72:73], v[156:157], v[80:81]
	global_store_dwordx4 v[88:89], v[76:79], off sc1
	global_store_dwordx4 v[88:89], v[72:75], off offset:16 sc1
	global_load_dwordx4 v[72:75], v[88:89], off offset:528
	s_nop 0
	global_load_dwordx4 v[76:79], v[88:89], off offset:512
	s_waitcnt vmcnt(1)
	v_pk_fma_f32 v[66:67], v[66:67], v[144:145], v[74:75]
	v_pk_fma_f32 v[64:65], v[64:65], v[146:147], v[72:73]
	global_store_dwordx4 v[88:89], v[64:67], off offset:528 sc1
	s_waitcnt vmcnt(1)
	v_pk_fma_f32 v[70:71], v[70:71], v[148:149], v[78:79]
	v_pk_fma_f32 v[68:69], v[68:69], v[150:151], v[76:77]
	v_add_u32_e32 v64, 0x180, v168
	v_ashrrev_i32_e32 v65, 31, v64
	v_lshlrev_b64 v[64:65], 12, v[64:65]
	v_lshl_add_u64 v[64:65], s[10:11], 0, v[64:65]
	global_store_dwordx4 v[88:89], v[68:71], off offset:512 sc1
	v_lshl_add_u64 v[72:73], v[64:65], 0, v[152:153]
	global_load_dwordx4 v[64:67], v[72:73], off offset:16
	global_load_dwordx4 v[68:71], v[72:73], off
	s_waitcnt vmcnt(1)
	v_pk_fma_f32 v[58:59], v[58:59], v[154:155], v[66:67]
	s_waitcnt vmcnt(0)
	v_pk_fma_f32 v[62:63], v[62:63], v[158:159], v[70:71]
	v_pk_fma_f32 v[60:61], v[60:61], v[160:161], v[68:69]
	v_pk_fma_f32 v[56:57], v[56:57], v[156:157], v[64:65]
	global_store_dwordx4 v[72:73], v[60:63], off sc1
	global_store_dwordx4 v[72:73], v[56:59], off offset:16 sc1
	global_load_dwordx4 v[56:59], v[72:73], off offset:528
	s_nop 0
	global_load_dwordx4 v[60:63], v[72:73], off offset:512
	s_waitcnt vmcnt(1)
	v_pk_fma_f32 v[50:51], v[50:51], v[144:145], v[58:59]
	v_pk_fma_f32 v[48:49], v[48:49], v[146:147], v[56:57]
	global_store_dwordx4 v[72:73], v[48:51], off offset:528 sc1
	s_waitcnt vmcnt(1)
	v_pk_fma_f32 v[54:55], v[54:55], v[148:149], v[62:63]
	v_pk_fma_f32 v[52:53], v[52:53], v[150:151], v[60:61]
	v_add_u32_e32 v48, 0x190, v168
	v_ashrrev_i32_e32 v49, 31, v48
	v_lshlrev_b64 v[48:49], 12, v[48:49]
	v_lshl_add_u64 v[48:49], s[10:11], 0, v[48:49]
	global_store_dwordx4 v[72:73], v[52:55], off offset:512 sc1
	v_lshl_add_u64 v[56:57], v[48:49], 0, v[152:153]
	global_load_dwordx4 v[48:51], v[56:57], off offset:16
	global_load_dwordx4 v[52:55], v[56:57], off
	s_waitcnt vmcnt(1)
	v_pk_fma_f32 v[42:43], v[42:43], v[154:155], v[50:51]
	s_waitcnt vmcnt(0)
	v_pk_fma_f32 v[46:47], v[46:47], v[158:159], v[54:55]
	v_pk_fma_f32 v[44:45], v[44:45], v[160:161], v[52:53]
	v_pk_fma_f32 v[40:41], v[40:41], v[156:157], v[48:49]
	global_store_dwordx4 v[56:57], v[44:47], off sc1
	global_store_dwordx4 v[56:57], v[40:43], off offset:16 sc1
	global_load_dwordx4 v[40:43], v[56:57], off offset:528
	s_nop 0
	global_load_dwordx4 v[44:47], v[56:57], off offset:512
	s_waitcnt vmcnt(1)
	v_pk_fma_f32 v[34:35], v[34:35], v[144:145], v[42:43]
	v_pk_fma_f32 v[32:33], v[32:33], v[146:147], v[40:41]
	global_store_dwordx4 v[56:57], v[32:35], off offset:528 sc1
	s_waitcnt vmcnt(1)
	v_pk_fma_f32 v[38:39], v[38:39], v[148:149], v[46:47]
	v_pk_fma_f32 v[36:37], v[36:37], v[150:151], v[44:45]
	v_add_u32_e32 v32, 0x1a0, v168
	v_ashrrev_i32_e32 v33, 31, v32
	v_lshlrev_b64 v[32:33], 12, v[32:33]
	v_lshl_add_u64 v[32:33], s[10:11], 0, v[32:33]
	global_store_dwordx4 v[56:57], v[36:39], off offset:512 sc1
	v_lshl_add_u64 v[40:41], v[32:33], 0, v[152:153]
	global_load_dwordx4 v[32:35], v[40:41], off offset:16
	global_load_dwordx4 v[36:39], v[40:41], off
	s_waitcnt vmcnt(1)
	v_pk_fma_f32 v[26:27], v[26:27], v[154:155], v[34:35]
	s_waitcnt vmcnt(0)
	v_pk_fma_f32 v[30:31], v[30:31], v[158:159], v[38:39]
	v_pk_fma_f32 v[28:29], v[28:29], v[160:161], v[36:37]
	v_pk_fma_f32 v[24:25], v[24:25], v[156:157], v[32:33]
	global_store_dwordx4 v[40:41], v[28:31], off sc1
	global_store_dwordx4 v[40:41], v[24:27], off offset:16 sc1
	global_load_dwordx4 v[24:27], v[40:41], off offset:528
	s_nop 0
	global_load_dwordx4 v[28:31], v[40:41], off offset:512
	s_waitcnt vmcnt(1)
	v_pk_fma_f32 v[18:19], v[18:19], v[144:145], v[26:27]
	v_pk_fma_f32 v[16:17], v[16:17], v[146:147], v[24:25]
	global_store_dwordx4 v[40:41], v[16:19], off offset:528 sc1
	s_waitcnt vmcnt(1)
	v_pk_fma_f32 v[22:23], v[22:23], v[148:149], v[30:31]
	v_pk_fma_f32 v[20:21], v[20:21], v[150:151], v[28:29]
	v_add_u32_e32 v16, 0x1b0, v168
	v_ashrrev_i32_e32 v17, 31, v16
	v_lshlrev_b64 v[16:17], 12, v[16:17]
	v_lshl_add_u64 v[16:17], s[10:11], 0, v[16:17]
	global_store_dwordx4 v[40:41], v[20:23], off offset:512 sc1
	v_lshl_add_u64 v[16:17], v[16:17], 0, v[152:153]
	global_load_dwordx4 v[18:21], v[16:17], off offset:16
	global_load_dwordx4 v[22:25], v[16:17], off
	s_waitcnt vmcnt(1)
	v_pk_fma_f32 v[10:11], v[10:11], v[154:155], v[20:21]
	s_waitcnt vmcnt(0)
	v_pk_fma_f32 v[14:15], v[14:15], v[158:159], v[24:25]
	v_pk_fma_f32 v[12:13], v[12:13], v[160:161], v[22:23]
	v_pk_fma_f32 v[8:9], v[8:9], v[156:157], v[18:19]
	global_store_dwordx4 v[16:17], v[12:15], off sc1
	global_store_dwordx4 v[16:17], v[8:11], off offset:16 sc1
	global_load_dwordx4 v[8:11], v[16:17], off offset:528
	s_nop 0
	global_load_dwordx4 v[12:15], v[16:17], off offset:512
	s_waitcnt vmcnt(1)
	v_pk_fma_f32 v[2:3], v[2:3], v[144:145], v[10:11]
	s_waitcnt vmcnt(0)
	v_pk_fma_f32 v[6:7], v[6:7], v[148:149], v[14:15]
	v_pk_fma_f32 v[4:5], v[4:5], v[150:151], v[12:13]
	v_pk_fma_f32 v[0:1], v[0:1], v[146:147], v[8:9]
	global_store_dwordx4 v[16:17], v[4:7], off offset:512 sc1
	global_store_dwordx4 v[16:17], v[0:3], off offset:528 sc1
	s_cbranch_vccnz .LBB0_2600
	s_andn2_b64 vcc, exec, s[12:13]
	s_cbranch_vccnz .LBB0_2599
	s_barrier
	s_branch .LBB0_2599
